# residual epilogues in two passes: pass A only loads (base rows three groups ahead) and forms xnew in the accumulators, pass B issues all stores, then the row reductions in two LDS round trips, then th
# speedup vs baseline: 1.0134x; 1.0016x over previous
.Lst_out_s2:
	v_lshl_add_u32 v215, s42, 8, v163
	v_add_u32_e32 v215, s30, v215
	v_lshlrev_b32_e32 v208, 2, v215
	v_lshl_add_u32 v212, v225, 3, s31
	v_lshl_add_u32 v212, s0, 8, v212
	v_lshl_add_u32 v209, v215, 11, v212
	v_lshlrev_b32_e32 v209, 1, v209
	v_lshlrev_b32_e32 v210, 1, v209
	v_lshl_add_u32 v215, v225, 4, v163
	v_xor_b32_e32 v213, 16, v215
	v_lshlrev_b32_e32 v213, 2, v213
	v_xor_b32_e32 v214, 32, v215
	v_lshlrev_b32_e32 v214, 2, v214
	v_add_u32_e32 v211, 0x0, v210
	global_load_dwordx4 v[176:179], v211, s[36:37]
	global_load_dwordx4 v[180:183], v211, s[36:37] offset:16
	global_load_dwordx4 v[184:187], v211, s[36:37] offset:512
	global_load_dwordx4 v[188:191], v211, s[36:37] offset:528
	v_add_u32_e32 v211, 0x20000, v210
	global_load_dwordx4 v[192:195], v211, s[36:37]
	global_load_dwordx4 v[196:199], v211, s[36:37] offset:16
	global_load_dwordx4 v[200:203], v211, s[36:37] offset:512
	global_load_dwordx4 v[204:207], v211, s[36:37] offset:528
	s_waitcnt vmcnt(4)
	v_pk_add_f32 v[124:125], v[124:125], v[176:177]
	v_pk_add_f32 v[126:127], v[126:127], v[178:179]
	v_pk_add_f32 v[120:121], v[120:121], v[180:181]
	v_pk_add_f32 v[122:123], v[122:123], v[182:183]
	v_pk_add_f32 v[116:117], v[116:117], v[184:185]
	v_pk_add_f32 v[118:119], v[118:119], v[186:187]
	v_pk_add_f32 v[112:113], v[112:113], v[188:189]
	v_pk_add_f32 v[114:115], v[114:115], v[190:191]
	v_add_u32_e32 v211, 0x40000, v210
	global_load_dwordx4 v[176:179], v211, s[36:37]
	global_load_dwordx4 v[180:183], v211, s[36:37] offset:16
	global_load_dwordx4 v[184:187], v211, s[36:37] offset:512
	global_load_dwordx4 v[188:191], v211, s[36:37] offset:528
	s_waitcnt vmcnt(4)
	v_pk_add_f32 v[108:109], v[108:109], v[192:193]
	v_pk_add_f32 v[110:111], v[110:111], v[194:195]
	v_pk_add_f32 v[104:105], v[104:105], v[196:197]
	v_pk_add_f32 v[106:107], v[106:107], v[198:199]
	v_pk_add_f32 v[100:101], v[100:101], v[200:201]
	v_pk_add_f32 v[102:103], v[102:103], v[202:203]
	v_pk_add_f32 v[96:97], v[96:97], v[204:205]
	v_pk_add_f32 v[98:99], v[98:99], v[206:207]
	v_add_u32_e32 v211, 0x60000, v210
	global_load_dwordx4 v[192:195], v211, s[36:37]
	global_load_dwordx4 v[196:199], v211, s[36:37] offset:16
	global_load_dwordx4 v[200:203], v211, s[36:37] offset:512
	global_load_dwordx4 v[204:207], v211, s[36:37] offset:528
	s_waitcnt vmcnt(4)
	v_pk_add_f32 v[92:93], v[92:93], v[176:177]
	v_pk_add_f32 v[94:95], v[94:95], v[178:179]
	v_pk_add_f32 v[88:89], v[88:89], v[180:181]
	v_pk_add_f32 v[90:91], v[90:91], v[182:183]
	v_pk_add_f32 v[84:85], v[84:85], v[184:185]
	v_pk_add_f32 v[86:87], v[86:87], v[186:187]
	v_pk_add_f32 v[80:81], v[80:81], v[188:189]
	v_pk_add_f32 v[82:83], v[82:83], v[190:191]
	v_add_u32_e32 v211, 0x100000, v210
	global_load_dwordx4 v[176:179], v211, s[36:37]
	global_load_dwordx4 v[180:183], v211, s[36:37] offset:16
	global_load_dwordx4 v[184:187], v211, s[36:37] offset:512
	global_load_dwordx4 v[188:191], v211, s[36:37] offset:528
	s_waitcnt vmcnt(4)
	v_pk_add_f32 v[76:77], v[76:77], v[192:193]
	v_pk_add_f32 v[78:79], v[78:79], v[194:195]
	v_pk_add_f32 v[72:73], v[72:73], v[196:197]
	v_pk_add_f32 v[74:75], v[74:75], v[198:199]
	v_pk_add_f32 v[68:69], v[68:69], v[200:201]
	v_pk_add_f32 v[70:71], v[70:71], v[202:203]
	v_pk_add_f32 v[64:65], v[64:65], v[204:205]
	v_pk_add_f32 v[66:67], v[66:67], v[206:207]
	v_add_u32_e32 v211, 0x120000, v210
	global_load_dwordx4 v[192:195], v211, s[36:37]
	global_load_dwordx4 v[196:199], v211, s[36:37] offset:16
	global_load_dwordx4 v[200:203], v211, s[36:37] offset:512
	global_load_dwordx4 v[204:207], v211, s[36:37] offset:528
	s_waitcnt vmcnt(4)
	v_pk_add_f32 v[60:61], v[60:61], v[176:177]
	v_pk_add_f32 v[62:63], v[62:63], v[178:179]
	v_pk_add_f32 v[56:57], v[56:57], v[180:181]
	v_pk_add_f32 v[58:59], v[58:59], v[182:183]
	v_pk_add_f32 v[52:53], v[52:53], v[184:185]
	v_pk_add_f32 v[54:55], v[54:55], v[186:187]
	v_pk_add_f32 v[48:49], v[48:49], v[188:189]
	v_pk_add_f32 v[50:51], v[50:51], v[190:191]
	v_add_u32_e32 v211, 0x140000, v210
	global_load_dwordx4 v[176:179], v211, s[36:37]
	global_load_dwordx4 v[180:183], v211, s[36:37] offset:16
	global_load_dwordx4 v[184:187], v211, s[36:37] offset:512
	global_load_dwordx4 v[188:191], v211, s[36:37] offset:528
	s_waitcnt vmcnt(4)
	v_pk_add_f32 v[44:45], v[44:45], v[192:193]
	v_pk_add_f32 v[46:47], v[46:47], v[194:195]
	v_pk_add_f32 v[40:41], v[40:41], v[196:197]
	v_pk_add_f32 v[42:43], v[42:43], v[198:199]
	v_pk_add_f32 v[36:37], v[36:37], v[200:201]
	v_pk_add_f32 v[38:39], v[38:39], v[202:203]
	v_pk_add_f32 v[32:33], v[32:33], v[204:205]
	v_pk_add_f32 v[34:35], v[34:35], v[206:207]
	v_add_u32_e32 v211, 0x160000, v210
	global_load_dwordx4 v[192:195], v211, s[36:37]
	global_load_dwordx4 v[196:199], v211, s[36:37] offset:16
	global_load_dwordx4 v[200:203], v211, s[36:37] offset:512
	global_load_dwordx4 v[204:207], v211, s[36:37] offset:528
	s_waitcnt vmcnt(4)
	v_pk_add_f32 v[28:29], v[28:29], v[176:177]
	v_pk_add_f32 v[30:31], v[30:31], v[178:179]
	v_pk_add_f32 v[24:25], v[24:25], v[180:181]
	v_pk_add_f32 v[26:27], v[26:27], v[182:183]
	v_pk_add_f32 v[20:21], v[20:21], v[184:185]
	v_pk_add_f32 v[22:23], v[22:23], v[186:187]
	v_pk_add_f32 v[16:17], v[16:17], v[188:189]
	v_pk_add_f32 v[18:19], v[18:19], v[190:191]
	s_waitcnt vmcnt(0)
	v_pk_add_f32 v[12:13], v[12:13], v[192:193]
	v_pk_add_f32 v[14:15], v[14:15], v[194:195]
	v_pk_add_f32 v[8:9], v[8:9], v[196:197]
	v_pk_add_f32 v[10:11], v[10:11], v[198:199]
	v_pk_add_f32 v[4:5], v[4:5], v[200:201]
	v_pk_add_f32 v[6:7], v[6:7], v[202:203]
	v_pk_add_f32 v[0:1], v[0:1], v[204:205]
	v_pk_add_f32 v[2:3], v[2:3], v[206:207]
	v_mul_f32_e32 v192, v124, v124
	v_fmac_f32_e32 v192, v125, v125
	v_fmac_f32_e32 v192, v126, v126
	v_fmac_f32_e32 v192, v127, v127
	v_fmac_f32_e32 v192, v120, v120
	v_fmac_f32_e32 v192, v121, v121
	v_fmac_f32_e32 v192, v122, v122
	v_fmac_f32_e32 v192, v123, v123
	v_fmac_f32_e32 v192, v116, v116
	v_fmac_f32_e32 v192, v117, v117
	v_fmac_f32_e32 v192, v118, v118
	v_fmac_f32_e32 v192, v119, v119
	v_fmac_f32_e32 v192, v112, v112
	v_fmac_f32_e32 v192, v113, v113
	v_fmac_f32_e32 v192, v114, v114
	v_fmac_f32_e32 v192, v115, v115
	v_add_u32_e32 v211, 0x0, v209
	v_cvt_pk_bf16_f32 v176, v124, v125
	v_cvt_pk_bf16_f32 v177, v126, v127
	v_cvt_pk_bf16_f32 v178, v120, v121
	v_cvt_pk_bf16_f32 v179, v122, v123
	global_store_dwordx4 v211, v[176:179], s[80:81]
	v_cvt_pk_bf16_f32 v180, v116, v117
	v_cvt_pk_bf16_f32 v181, v118, v119
	v_cvt_pk_bf16_f32 v182, v112, v113
	v_cvt_pk_bf16_f32 v183, v114, v115
	global_store_dwordx4 v211, v[180:183], s[80:81] offset:256
	v_mul_f32_e32 v193, v108, v108
	v_fmac_f32_e32 v193, v109, v109
	v_fmac_f32_e32 v193, v110, v110
	v_fmac_f32_e32 v193, v111, v111
	v_fmac_f32_e32 v193, v104, v104
	v_fmac_f32_e32 v193, v105, v105
	v_fmac_f32_e32 v193, v106, v106
	v_fmac_f32_e32 v193, v107, v107
	v_fmac_f32_e32 v193, v100, v100
	v_fmac_f32_e32 v193, v101, v101
	v_fmac_f32_e32 v193, v102, v102
	v_fmac_f32_e32 v193, v103, v103
	v_fmac_f32_e32 v193, v96, v96
	v_fmac_f32_e32 v193, v97, v97
	v_fmac_f32_e32 v193, v98, v98
	v_fmac_f32_e32 v193, v99, v99
	v_add_u32_e32 v211, 0x10000, v209
	v_cvt_pk_bf16_f32 v184, v108, v109
	v_cvt_pk_bf16_f32 v185, v110, v111
	v_cvt_pk_bf16_f32 v186, v104, v105
	v_cvt_pk_bf16_f32 v187, v106, v107
	global_store_dwordx4 v211, v[184:187], s[80:81]
	v_cvt_pk_bf16_f32 v188, v100, v101
	v_cvt_pk_bf16_f32 v189, v102, v103
	v_cvt_pk_bf16_f32 v190, v96, v97
	v_cvt_pk_bf16_f32 v191, v98, v99
	global_store_dwordx4 v211, v[188:191], s[80:81] offset:256
	v_mul_f32_e32 v194, v92, v92
	v_fmac_f32_e32 v194, v93, v93
	v_fmac_f32_e32 v194, v94, v94
	v_fmac_f32_e32 v194, v95, v95
	v_fmac_f32_e32 v194, v88, v88
	v_fmac_f32_e32 v194, v89, v89
	v_fmac_f32_e32 v194, v90, v90
	v_fmac_f32_e32 v194, v91, v91
	v_fmac_f32_e32 v194, v84, v84
	v_fmac_f32_e32 v194, v85, v85
	v_fmac_f32_e32 v194, v86, v86
	v_fmac_f32_e32 v194, v87, v87
	v_fmac_f32_e32 v194, v80, v80
	v_fmac_f32_e32 v194, v81, v81
	v_fmac_f32_e32 v194, v82, v82
	v_fmac_f32_e32 v194, v83, v83
	v_add_u32_e32 v211, 0x20000, v209
	v_cvt_pk_bf16_f32 v176, v92, v93
	v_cvt_pk_bf16_f32 v177, v94, v95
	v_cvt_pk_bf16_f32 v178, v88, v89
	v_cvt_pk_bf16_f32 v179, v90, v91
	global_store_dwordx4 v211, v[176:179], s[80:81]
	v_cvt_pk_bf16_f32 v180, v84, v85
	v_cvt_pk_bf16_f32 v181, v86, v87
	v_cvt_pk_bf16_f32 v182, v80, v81
	v_cvt_pk_bf16_f32 v183, v82, v83
	global_store_dwordx4 v211, v[180:183], s[80:81] offset:256
	v_mul_f32_e32 v195, v76, v76
	v_fmac_f32_e32 v195, v77, v77
	v_fmac_f32_e32 v195, v78, v78
	v_fmac_f32_e32 v195, v79, v79
	v_fmac_f32_e32 v195, v72, v72
	v_fmac_f32_e32 v195, v73, v73
	v_fmac_f32_e32 v195, v74, v74
	v_fmac_f32_e32 v195, v75, v75
	v_fmac_f32_e32 v195, v68, v68
	v_fmac_f32_e32 v195, v69, v69
	v_fmac_f32_e32 v195, v70, v70
	v_fmac_f32_e32 v195, v71, v71
	v_fmac_f32_e32 v195, v64, v64
	v_fmac_f32_e32 v195, v65, v65
	v_fmac_f32_e32 v195, v66, v66
	v_fmac_f32_e32 v195, v67, v67
	v_add_u32_e32 v211, 0x30000, v209
	v_cvt_pk_bf16_f32 v184, v76, v77
	v_cvt_pk_bf16_f32 v185, v78, v79
	v_cvt_pk_bf16_f32 v186, v72, v73
	v_cvt_pk_bf16_f32 v187, v74, v75
	global_store_dwordx4 v211, v[184:187], s[80:81]
	v_cvt_pk_bf16_f32 v188, v68, v69
	v_cvt_pk_bf16_f32 v189, v70, v71
	v_cvt_pk_bf16_f32 v190, v64, v65
	v_cvt_pk_bf16_f32 v191, v66, v67
	global_store_dwordx4 v211, v[188:191], s[80:81] offset:256
	v_mul_f32_e32 v196, v60, v60
	v_fmac_f32_e32 v196, v61, v61
	v_fmac_f32_e32 v196, v62, v62
	v_fmac_f32_e32 v196, v63, v63
	v_fmac_f32_e32 v196, v56, v56
	v_fmac_f32_e32 v196, v57, v57
	v_fmac_f32_e32 v196, v58, v58
	v_fmac_f32_e32 v196, v59, v59
	v_fmac_f32_e32 v196, v52, v52
	v_fmac_f32_e32 v196, v53, v53
	v_fmac_f32_e32 v196, v54, v54
	v_fmac_f32_e32 v196, v55, v55
	v_fmac_f32_e32 v196, v48, v48
	v_fmac_f32_e32 v196, v49, v49
	v_fmac_f32_e32 v196, v50, v50
	v_fmac_f32_e32 v196, v51, v51
	v_add_u32_e32 v211, 0x80000, v209
	v_cvt_pk_bf16_f32 v176, v60, v61
	v_cvt_pk_bf16_f32 v177, v62, v63
	v_cvt_pk_bf16_f32 v178, v56, v57
	v_cvt_pk_bf16_f32 v179, v58, v59
	global_store_dwordx4 v211, v[176:179], s[80:81]
	v_cvt_pk_bf16_f32 v180, v52, v53
	v_cvt_pk_bf16_f32 v181, v54, v55
	v_cvt_pk_bf16_f32 v182, v48, v49
	v_cvt_pk_bf16_f32 v183, v50, v51
	global_store_dwordx4 v211, v[180:183], s[80:81] offset:256
	v_mul_f32_e32 v197, v44, v44
	v_fmac_f32_e32 v197, v45, v45
	v_fmac_f32_e32 v197, v46, v46
	v_fmac_f32_e32 v197, v47, v47
	v_fmac_f32_e32 v197, v40, v40
	v_fmac_f32_e32 v197, v41, v41
	v_fmac_f32_e32 v197, v42, v42
	v_fmac_f32_e32 v197, v43, v43
	v_fmac_f32_e32 v197, v36, v36
	v_fmac_f32_e32 v197, v37, v37
	v_fmac_f32_e32 v197, v38, v38
	v_fmac_f32_e32 v197, v39, v39
	v_fmac_f32_e32 v197, v32, v32
	v_fmac_f32_e32 v197, v33, v33
	v_fmac_f32_e32 v197, v34, v34
	v_fmac_f32_e32 v197, v35, v35
	v_add_u32_e32 v211, 0x90000, v209
	v_cvt_pk_bf16_f32 v184, v44, v45
	v_cvt_pk_bf16_f32 v185, v46, v47
	v_cvt_pk_bf16_f32 v186, v40, v41
	v_cvt_pk_bf16_f32 v187, v42, v43
	global_store_dwordx4 v211, v[184:187], s[80:81]
	v_cvt_pk_bf16_f32 v188, v36, v37
	v_cvt_pk_bf16_f32 v189, v38, v39
	v_cvt_pk_bf16_f32 v190, v32, v33
	v_cvt_pk_bf16_f32 v191, v34, v35
	global_store_dwordx4 v211, v[188:191], s[80:81] offset:256
	v_mul_f32_e32 v198, v28, v28
	v_fmac_f32_e32 v198, v29, v29
	v_fmac_f32_e32 v198, v30, v30
	v_fmac_f32_e32 v198, v31, v31
	v_fmac_f32_e32 v198, v24, v24
	v_fmac_f32_e32 v198, v25, v25
	v_fmac_f32_e32 v198, v26, v26
	v_fmac_f32_e32 v198, v27, v27
	v_fmac_f32_e32 v198, v20, v20
	v_fmac_f32_e32 v198, v21, v21
	v_fmac_f32_e32 v198, v22, v22
	v_fmac_f32_e32 v198, v23, v23
	v_fmac_f32_e32 v198, v16, v16
	v_fmac_f32_e32 v198, v17, v17
	v_fmac_f32_e32 v198, v18, v18
	v_fmac_f32_e32 v198, v19, v19
	v_add_u32_e32 v211, 0xa0000, v209
	v_cvt_pk_bf16_f32 v176, v28, v29
	v_cvt_pk_bf16_f32 v177, v30, v31
	v_cvt_pk_bf16_f32 v178, v24, v25
	v_cvt_pk_bf16_f32 v179, v26, v27
	global_store_dwordx4 v211, v[176:179], s[80:81]
	v_cvt_pk_bf16_f32 v180, v20, v21
	v_cvt_pk_bf16_f32 v181, v22, v23
	v_cvt_pk_bf16_f32 v182, v16, v17
	v_cvt_pk_bf16_f32 v183, v18, v19
	global_store_dwordx4 v211, v[180:183], s[80:81] offset:256
	v_mul_f32_e32 v199, v12, v12
	v_fmac_f32_e32 v199, v13, v13
	v_fmac_f32_e32 v199, v14, v14
	v_fmac_f32_e32 v199, v15, v15
	v_fmac_f32_e32 v199, v8, v8
	v_fmac_f32_e32 v199, v9, v9
	v_fmac_f32_e32 v199, v10, v10
	v_fmac_f32_e32 v199, v11, v11
	v_fmac_f32_e32 v199, v4, v4
	v_fmac_f32_e32 v199, v5, v5
	v_fmac_f32_e32 v199, v6, v6
	v_fmac_f32_e32 v199, v7, v7
	v_fmac_f32_e32 v199, v0, v0
	v_fmac_f32_e32 v199, v1, v1
	v_fmac_f32_e32 v199, v2, v2
	v_fmac_f32_e32 v199, v3, v3
	v_add_u32_e32 v211, 0xb0000, v209
	v_cvt_pk_bf16_f32 v184, v12, v13
	v_cvt_pk_bf16_f32 v185, v14, v15
	v_cvt_pk_bf16_f32 v186, v8, v9
	v_cvt_pk_bf16_f32 v187, v10, v11
	global_store_dwordx4 v211, v[184:187], s[80:81]
	v_cvt_pk_bf16_f32 v188, v4, v5
	v_cvt_pk_bf16_f32 v189, v6, v7
	v_cvt_pk_bf16_f32 v190, v0, v1
	v_cvt_pk_bf16_f32 v191, v2, v3
	global_store_dwordx4 v211, v[188:191], s[80:81] offset:256
	s_nop 1
	ds_bpermute_b32 v200, v213, v192
	ds_bpermute_b32 v201, v213, v193
	ds_bpermute_b32 v202, v213, v194
	ds_bpermute_b32 v203, v213, v195
	ds_bpermute_b32 v204, v213, v196
	ds_bpermute_b32 v205, v213, v197
	ds_bpermute_b32 v206, v213, v198
	ds_bpermute_b32 v207, v213, v199
	s_waitcnt lgkmcnt(0)
	v_add_f32_e32 v192, v192, v200
	v_add_f32_e32 v193, v193, v201
	v_add_f32_e32 v194, v194, v202
	v_add_f32_e32 v195, v195, v203
	v_add_f32_e32 v196, v196, v204
	v_add_f32_e32 v197, v197, v205
	v_add_f32_e32 v198, v198, v206
	v_add_f32_e32 v199, v199, v207
	ds_bpermute_b32 v200, v214, v192
	ds_bpermute_b32 v201, v214, v193
	ds_bpermute_b32 v202, v214, v194
	ds_bpermute_b32 v203, v214, v195
	ds_bpermute_b32 v204, v214, v196
	ds_bpermute_b32 v205, v214, v197
	ds_bpermute_b32 v206, v214, v198
	ds_bpermute_b32 v207, v214, v199
	s_waitcnt lgkmcnt(0)
	v_add_f32_e32 v192, v192, v200
	v_add_f32_e32 v193, v193, v201
	v_add_f32_e32 v194, v194, v202
	v_add_f32_e32 v195, v195, v203
	v_add_f32_e32 v196, v196, v204
	v_add_f32_e32 v197, v197, v205
	v_add_f32_e32 v198, v198, v206
	v_add_f32_e32 v199, v199, v207
	s_mov_b64 exec, 0xffff
	global_atomic_add_f32 v208, v192, s[12:13]
	global_atomic_add_f32 v208, v193, s[12:13] offset:64
	global_atomic_add_f32 v208, v194, s[12:13] offset:128
	global_atomic_add_f32 v208, v195, s[12:13] offset:192
	global_atomic_add_f32 v208, v196, s[12:13] offset:512
	global_atomic_add_f32 v208, v197, s[12:13] offset:576
	global_atomic_add_f32 v208, v198, s[12:13] offset:640
	global_atomic_add_f32 v208, v199, s[12:13] offset:704
	s_mov_b64 exec, -1
	s_branch .LBB0_273

.Lst_out_s4:
	v_lshl_add_u32 v215, s38, 8, v163
	v_add_u32_e32 v215, s26, v215
	v_lshlrev_b32_e32 v208, 2, v215
	v_lshl_add_u32 v212, v225, 3, s27
	v_lshl_add_u32 v212, s37, 8, v212
	v_lshl_add_u32 v209, v215, 11, v212
	v_lshlrev_b32_e32 v209, 1, v209
	v_lshlrev_b32_e32 v210, 1, v209
	v_lshl_add_u32 v215, v225, 4, v163
	v_xor_b32_e32 v213, 16, v215
	v_lshlrev_b32_e32 v213, 2, v213
	v_xor_b32_e32 v214, 32, v215
	v_lshlrev_b32_e32 v214, 2, v214
	v_add_u32_e32 v211, 0x0, v209
	global_load_dwordx4 v[176:179], v211, s[80:81]
	global_load_dwordx4 v[180:183], v211, s[80:81] offset:256
	v_add_u32_e32 v211, 0x10000, v209
	global_load_dwordx4 v[184:187], v211, s[80:81]
	global_load_dwordx4 v[188:191], v211, s[80:81] offset:256
	v_add_u32_e32 v211, 0x20000, v209
	global_load_dwordx4 v[192:195], v211, s[80:81]
	global_load_dwordx4 v[196:199], v211, s[80:81] offset:256
	s_waitcnt vmcnt(4)
	v_lshlrev_b32_e32 v200, 16, v176
	v_and_b32_e32 v201, 0xffff0000, v176
	v_lshlrev_b32_e32 v202, 16, v177
	v_and_b32_e32 v203, 0xffff0000, v177
	v_lshlrev_b32_e32 v204, 16, v178
	v_and_b32_e32 v205, 0xffff0000, v178
	v_lshlrev_b32_e32 v206, 16, v179
	v_and_b32_e32 v207, 0xffff0000, v179
	v_pk_add_f32 v[124:125], v[124:125], v[200:201]
	v_pk_add_f32 v[126:127], v[126:127], v[202:203]
	v_pk_add_f32 v[120:121], v[120:121], v[204:205]
	v_pk_add_f32 v[122:123], v[122:123], v[206:207]
	v_lshlrev_b32_e32 v200, 16, v180
	v_and_b32_e32 v201, 0xffff0000, v180
	v_lshlrev_b32_e32 v202, 16, v181
	v_and_b32_e32 v203, 0xffff0000, v181
	v_lshlrev_b32_e32 v204, 16, v182
	v_and_b32_e32 v205, 0xffff0000, v182
	v_lshlrev_b32_e32 v206, 16, v183
	v_and_b32_e32 v207, 0xffff0000, v183
	v_pk_add_f32 v[116:117], v[116:117], v[200:201]
	v_pk_add_f32 v[118:119], v[118:119], v[202:203]
	v_pk_add_f32 v[112:113], v[112:113], v[204:205]
	v_pk_add_f32 v[114:115], v[114:115], v[206:207]
	v_add_u32_e32 v211, 0x30000, v209
	global_load_dwordx4 v[176:179], v211, s[80:81]
	global_load_dwordx4 v[180:183], v211, s[80:81] offset:256
	s_waitcnt vmcnt(4)
	v_lshlrev_b32_e32 v200, 16, v184
	v_and_b32_e32 v201, 0xffff0000, v184
	v_lshlrev_b32_e32 v202, 16, v185
	v_and_b32_e32 v203, 0xffff0000, v185
	v_lshlrev_b32_e32 v204, 16, v186
	v_and_b32_e32 v205, 0xffff0000, v186
	v_lshlrev_b32_e32 v206, 16, v187
	v_and_b32_e32 v207, 0xffff0000, v187
	v_pk_add_f32 v[108:109], v[108:109], v[200:201]
	v_pk_add_f32 v[110:111], v[110:111], v[202:203]
	v_pk_add_f32 v[104:105], v[104:105], v[204:205]
	v_pk_add_f32 v[106:107], v[106:107], v[206:207]
	v_lshlrev_b32_e32 v200, 16, v188
	v_and_b32_e32 v201, 0xffff0000, v188
	v_lshlrev_b32_e32 v202, 16, v189
	v_and_b32_e32 v203, 0xffff0000, v189
	v_lshlrev_b32_e32 v204, 16, v190
	v_and_b32_e32 v205, 0xffff0000, v190
	v_lshlrev_b32_e32 v206, 16, v191
	v_and_b32_e32 v207, 0xffff0000, v191
	v_pk_add_f32 v[100:101], v[100:101], v[200:201]
	v_pk_add_f32 v[102:103], v[102:103], v[202:203]
	v_pk_add_f32 v[96:97], v[96:97], v[204:205]
	v_pk_add_f32 v[98:99], v[98:99], v[206:207]
	v_add_u32_e32 v211, 0x80000, v209
	global_load_dwordx4 v[184:187], v211, s[80:81]
	global_load_dwordx4 v[188:191], v211, s[80:81] offset:256
	s_waitcnt vmcnt(4)
	v_lshlrev_b32_e32 v200, 16, v192
	v_and_b32_e32 v201, 0xffff0000, v192
	v_lshlrev_b32_e32 v202, 16, v193
	v_and_b32_e32 v203, 0xffff0000, v193
	v_lshlrev_b32_e32 v204, 16, v194
	v_and_b32_e32 v205, 0xffff0000, v194
	v_lshlrev_b32_e32 v206, 16, v195
	v_and_b32_e32 v207, 0xffff0000, v195
	v_pk_add_f32 v[92:93], v[92:93], v[200:201]
	v_pk_add_f32 v[94:95], v[94:95], v[202:203]
	v_pk_add_f32 v[88:89], v[88:89], v[204:205]
	v_pk_add_f32 v[90:91], v[90:91], v[206:207]
	v_lshlrev_b32_e32 v200, 16, v196
	v_and_b32_e32 v201, 0xffff0000, v196
	v_lshlrev_b32_e32 v202, 16, v197
	v_and_b32_e32 v203, 0xffff0000, v197
	v_lshlrev_b32_e32 v204, 16, v198
	v_and_b32_e32 v205, 0xffff0000, v198
	v_lshlrev_b32_e32 v206, 16, v199
	v_and_b32_e32 v207, 0xffff0000, v199
	v_pk_add_f32 v[84:85], v[84:85], v[200:201]
	v_pk_add_f32 v[86:87], v[86:87], v[202:203]
	v_pk_add_f32 v[80:81], v[80:81], v[204:205]
	v_pk_add_f32 v[82:83], v[82:83], v[206:207]
	v_add_u32_e32 v211, 0x90000, v209
	global_load_dwordx4 v[192:195], v211, s[80:81]
	global_load_dwordx4 v[196:199], v211, s[80:81] offset:256
	s_waitcnt vmcnt(4)
	v_lshlrev_b32_e32 v200, 16, v176
	v_and_b32_e32 v201, 0xffff0000, v176
	v_lshlrev_b32_e32 v202, 16, v177
	v_and_b32_e32 v203, 0xffff0000, v177
	v_lshlrev_b32_e32 v204, 16, v178
	v_and_b32_e32 v205, 0xffff0000, v178
	v_lshlrev_b32_e32 v206, 16, v179
	v_and_b32_e32 v207, 0xffff0000, v179
	v_pk_add_f32 v[76:77], v[76:77], v[200:201]
	v_pk_add_f32 v[78:79], v[78:79], v[202:203]
	v_pk_add_f32 v[72:73], v[72:73], v[204:205]
	v_pk_add_f32 v[74:75], v[74:75], v[206:207]
	v_lshlrev_b32_e32 v200, 16, v180
	v_and_b32_e32 v201, 0xffff0000, v180
	v_lshlrev_b32_e32 v202, 16, v181
	v_and_b32_e32 v203, 0xffff0000, v181
	v_lshlrev_b32_e32 v204, 16, v182
	v_and_b32_e32 v205, 0xffff0000, v182
	v_lshlrev_b32_e32 v206, 16, v183
	v_and_b32_e32 v207, 0xffff0000, v183
	v_pk_add_f32 v[68:69], v[68:69], v[200:201]
	v_pk_add_f32 v[70:71], v[70:71], v[202:203]
	v_pk_add_f32 v[64:65], v[64:65], v[204:205]
	v_pk_add_f32 v[66:67], v[66:67], v[206:207]
	v_add_u32_e32 v211, 0xa0000, v209
	global_load_dwordx4 v[176:179], v211, s[80:81]
	global_load_dwordx4 v[180:183], v211, s[80:81] offset:256
	s_waitcnt vmcnt(4)
	v_lshlrev_b32_e32 v200, 16, v184
	v_and_b32_e32 v201, 0xffff0000, v184
	v_lshlrev_b32_e32 v202, 16, v185
	v_and_b32_e32 v203, 0xffff0000, v185
	v_lshlrev_b32_e32 v204, 16, v186
	v_and_b32_e32 v205, 0xffff0000, v186
	v_lshlrev_b32_e32 v206, 16, v187
	v_and_b32_e32 v207, 0xffff0000, v187
	v_pk_add_f32 v[60:61], v[60:61], v[200:201]
	v_pk_add_f32 v[62:63], v[62:63], v[202:203]
	v_pk_add_f32 v[56:57], v[56:57], v[204:205]
	v_pk_add_f32 v[58:59], v[58:59], v[206:207]
	v_lshlrev_b32_e32 v200, 16, v188
	v_and_b32_e32 v201, 0xffff0000, v188
	v_lshlrev_b32_e32 v202, 16, v189
	v_and_b32_e32 v203, 0xffff0000, v189
	v_lshlrev_b32_e32 v204, 16, v190
	v_and_b32_e32 v205, 0xffff0000, v190
	v_lshlrev_b32_e32 v206, 16, v191
	v_and_b32_e32 v207, 0xffff0000, v191
	v_pk_add_f32 v[52:53], v[52:53], v[200:201]
	v_pk_add_f32 v[54:55], v[54:55], v[202:203]
	v_pk_add_f32 v[48:49], v[48:49], v[204:205]
	v_pk_add_f32 v[50:51], v[50:51], v[206:207]
	v_add_u32_e32 v211, 0xb0000, v209
	global_load_dwordx4 v[184:187], v211, s[80:81]
	global_load_dwordx4 v[188:191], v211, s[80:81] offset:256
	s_waitcnt vmcnt(4)
	v_lshlrev_b32_e32 v200, 16, v192
	v_and_b32_e32 v201, 0xffff0000, v192
	v_lshlrev_b32_e32 v202, 16, v193
	v_and_b32_e32 v203, 0xffff0000, v193
	v_lshlrev_b32_e32 v204, 16, v194
	v_and_b32_e32 v205, 0xffff0000, v194
	v_lshlrev_b32_e32 v206, 16, v195
	v_and_b32_e32 v207, 0xffff0000, v195
	v_pk_add_f32 v[44:45], v[44:45], v[200:201]
	v_pk_add_f32 v[46:47], v[46:47], v[202:203]
	v_pk_add_f32 v[40:41], v[40:41], v[204:205]
	v_pk_add_f32 v[42:43], v[42:43], v[206:207]
	v_lshlrev_b32_e32 v200, 16, v196
	v_and_b32_e32 v201, 0xffff0000, v196
	v_lshlrev_b32_e32 v202, 16, v197
	v_and_b32_e32 v203, 0xffff0000, v197
	v_lshlrev_b32_e32 v204, 16, v198
	v_and_b32_e32 v205, 0xffff0000, v198
	v_lshlrev_b32_e32 v206, 16, v199
	v_and_b32_e32 v207, 0xffff0000, v199
	v_pk_add_f32 v[36:37], v[36:37], v[200:201]
	v_pk_add_f32 v[38:39], v[38:39], v[202:203]
	v_pk_add_f32 v[32:33], v[32:33], v[204:205]
	v_pk_add_f32 v[34:35], v[34:35], v[206:207]
	s_waitcnt vmcnt(2)
	v_lshlrev_b32_e32 v200, 16, v176
	v_and_b32_e32 v201, 0xffff0000, v176
	v_lshlrev_b32_e32 v202, 16, v177
	v_and_b32_e32 v203, 0xffff0000, v177
	v_lshlrev_b32_e32 v204, 16, v178
	v_and_b32_e32 v205, 0xffff0000, v178
	v_lshlrev_b32_e32 v206, 16, v179
	v_and_b32_e32 v207, 0xffff0000, v179
	v_pk_add_f32 v[28:29], v[28:29], v[200:201]
	v_pk_add_f32 v[30:31], v[30:31], v[202:203]
	v_pk_add_f32 v[24:25], v[24:25], v[204:205]
	v_pk_add_f32 v[26:27], v[26:27], v[206:207]
	v_lshlrev_b32_e32 v200, 16, v180
	v_and_b32_e32 v201, 0xffff0000, v180
	v_lshlrev_b32_e32 v202, 16, v181
	v_and_b32_e32 v203, 0xffff0000, v181
	v_lshlrev_b32_e32 v204, 16, v182
	v_and_b32_e32 v205, 0xffff0000, v182
	v_lshlrev_b32_e32 v206, 16, v183
	v_and_b32_e32 v207, 0xffff0000, v183
	v_pk_add_f32 v[20:21], v[20:21], v[200:201]
	v_pk_add_f32 v[22:23], v[22:23], v[202:203]
	v_pk_add_f32 v[16:17], v[16:17], v[204:205]
	v_pk_add_f32 v[18:19], v[18:19], v[206:207]
	s_waitcnt vmcnt(0)
	v_lshlrev_b32_e32 v200, 16, v184
	v_and_b32_e32 v201, 0xffff0000, v184
	v_lshlrev_b32_e32 v202, 16, v185
	v_and_b32_e32 v203, 0xffff0000, v185
	v_lshlrev_b32_e32 v204, 16, v186
	v_and_b32_e32 v205, 0xffff0000, v186
	v_lshlrev_b32_e32 v206, 16, v187
	v_and_b32_e32 v207, 0xffff0000, v187
	v_pk_add_f32 v[12:13], v[12:13], v[200:201]
	v_pk_add_f32 v[14:15], v[14:15], v[202:203]
	v_pk_add_f32 v[8:9], v[8:9], v[204:205]
	v_pk_add_f32 v[10:11], v[10:11], v[206:207]
	v_lshlrev_b32_e32 v200, 16, v188
	v_and_b32_e32 v201, 0xffff0000, v188
	v_lshlrev_b32_e32 v202, 16, v189
	v_and_b32_e32 v203, 0xffff0000, v189
	v_lshlrev_b32_e32 v204, 16, v190
	v_and_b32_e32 v205, 0xffff0000, v190
	v_lshlrev_b32_e32 v206, 16, v191
	v_and_b32_e32 v207, 0xffff0000, v191
	v_pk_add_f32 v[4:5], v[4:5], v[200:201]
	v_pk_add_f32 v[6:7], v[6:7], v[202:203]
	v_pk_add_f32 v[0:1], v[0:1], v[204:205]
	v_pk_add_f32 v[2:3], v[2:3], v[206:207]
	v_mul_f32_e32 v200, v124, v124
	v_fmac_f32_e32 v200, v125, v125
	v_fmac_f32_e32 v200, v126, v126
	v_fmac_f32_e32 v200, v127, v127
	v_fmac_f32_e32 v200, v120, v120
	v_fmac_f32_e32 v200, v121, v121
	v_fmac_f32_e32 v200, v122, v122
	v_fmac_f32_e32 v200, v123, v123
	v_fmac_f32_e32 v200, v116, v116
	v_fmac_f32_e32 v200, v117, v117
	v_fmac_f32_e32 v200, v118, v118
	v_fmac_f32_e32 v200, v119, v119
	v_fmac_f32_e32 v200, v112, v112
	v_fmac_f32_e32 v200, v113, v113
	v_fmac_f32_e32 v200, v114, v114
	v_fmac_f32_e32 v200, v115, v115
	v_add_u32_e32 v211, 0x0, v209
	v_cvt_pk_bf16_f32 v176, v124, v125
	v_cvt_pk_bf16_f32 v177, v126, v127
	v_cvt_pk_bf16_f32 v178, v120, v121
	v_cvt_pk_bf16_f32 v179, v122, v123
	global_store_dwordx4 v211, v[176:179], s[80:81]
	v_cvt_pk_bf16_f32 v180, v116, v117
	v_cvt_pk_bf16_f32 v181, v118, v119
	v_cvt_pk_bf16_f32 v182, v112, v113
	v_cvt_pk_bf16_f32 v183, v114, v115
	global_store_dwordx4 v211, v[180:183], s[80:81] offset:256
	v_mul_f32_e32 v201, v108, v108
	v_fmac_f32_e32 v201, v109, v109
	v_fmac_f32_e32 v201, v110, v110
	v_fmac_f32_e32 v201, v111, v111
	v_fmac_f32_e32 v201, v104, v104
	v_fmac_f32_e32 v201, v105, v105
	v_fmac_f32_e32 v201, v106, v106
	v_fmac_f32_e32 v201, v107, v107
	v_fmac_f32_e32 v201, v100, v100
	v_fmac_f32_e32 v201, v101, v101
	v_fmac_f32_e32 v201, v102, v102
	v_fmac_f32_e32 v201, v103, v103
	v_fmac_f32_e32 v201, v96, v96
	v_fmac_f32_e32 v201, v97, v97
	v_fmac_f32_e32 v201, v98, v98
	v_fmac_f32_e32 v201, v99, v99
	v_add_u32_e32 v211, 0x10000, v209
	v_cvt_pk_bf16_f32 v184, v108, v109
	v_cvt_pk_bf16_f32 v185, v110, v111
	v_cvt_pk_bf16_f32 v186, v104, v105
	v_cvt_pk_bf16_f32 v187, v106, v107
	global_store_dwordx4 v211, v[184:187], s[80:81]
	v_cvt_pk_bf16_f32 v188, v100, v101
	v_cvt_pk_bf16_f32 v189, v102, v103
	v_cvt_pk_bf16_f32 v190, v96, v97
	v_cvt_pk_bf16_f32 v191, v98, v99
	global_store_dwordx4 v211, v[188:191], s[80:81] offset:256
	v_mul_f32_e32 v202, v92, v92
	v_fmac_f32_e32 v202, v93, v93
	v_fmac_f32_e32 v202, v94, v94
	v_fmac_f32_e32 v202, v95, v95
	v_fmac_f32_e32 v202, v88, v88
	v_fmac_f32_e32 v202, v89, v89
	v_fmac_f32_e32 v202, v90, v90
	v_fmac_f32_e32 v202, v91, v91
	v_fmac_f32_e32 v202, v84, v84
	v_fmac_f32_e32 v202, v85, v85
	v_fmac_f32_e32 v202, v86, v86
	v_fmac_f32_e32 v202, v87, v87
	v_fmac_f32_e32 v202, v80, v80
	v_fmac_f32_e32 v202, v81, v81
	v_fmac_f32_e32 v202, v82, v82
	v_fmac_f32_e32 v202, v83, v83
	v_add_u32_e32 v211, 0x20000, v209
	v_cvt_pk_bf16_f32 v176, v92, v93
	v_cvt_pk_bf16_f32 v177, v94, v95
	v_cvt_pk_bf16_f32 v178, v88, v89
	v_cvt_pk_bf16_f32 v179, v90, v91
	global_store_dwordx4 v211, v[176:179], s[80:81]
	v_cvt_pk_bf16_f32 v180, v84, v85
	v_cvt_pk_bf16_f32 v181, v86, v87
	v_cvt_pk_bf16_f32 v182, v80, v81
	v_cvt_pk_bf16_f32 v183, v82, v83
	global_store_dwordx4 v211, v[180:183], s[80:81] offset:256
	v_mul_f32_e32 v203, v76, v76
	v_fmac_f32_e32 v203, v77, v77
	v_fmac_f32_e32 v203, v78, v78
	v_fmac_f32_e32 v203, v79, v79
	v_fmac_f32_e32 v203, v72, v72
	v_fmac_f32_e32 v203, v73, v73
	v_fmac_f32_e32 v203, v74, v74
	v_fmac_f32_e32 v203, v75, v75
	v_fmac_f32_e32 v203, v68, v68
	v_fmac_f32_e32 v203, v69, v69
	v_fmac_f32_e32 v203, v70, v70
	v_fmac_f32_e32 v203, v71, v71
	v_fmac_f32_e32 v203, v64, v64
	v_fmac_f32_e32 v203, v65, v65
	v_fmac_f32_e32 v203, v66, v66
	v_fmac_f32_e32 v203, v67, v67
	v_add_u32_e32 v211, 0x30000, v209
	v_cvt_pk_bf16_f32 v184, v76, v77
	v_cvt_pk_bf16_f32 v185, v78, v79
	v_cvt_pk_bf16_f32 v186, v72, v73
	v_cvt_pk_bf16_f32 v187, v74, v75
	global_store_dwordx4 v211, v[184:187], s[80:81]
	v_cvt_pk_bf16_f32 v188, v68, v69
	v_cvt_pk_bf16_f32 v189, v70, v71
	v_cvt_pk_bf16_f32 v190, v64, v65
	v_cvt_pk_bf16_f32 v191, v66, v67
	global_store_dwordx4 v211, v[188:191], s[80:81] offset:256
	v_mul_f32_e32 v204, v60, v60
	v_fmac_f32_e32 v204, v61, v61
	v_fmac_f32_e32 v204, v62, v62
	v_fmac_f32_e32 v204, v63, v63
	v_fmac_f32_e32 v204, v56, v56
	v_fmac_f32_e32 v204, v57, v57
	v_fmac_f32_e32 v204, v58, v58
	v_fmac_f32_e32 v204, v59, v59
	v_fmac_f32_e32 v204, v52, v52
	v_fmac_f32_e32 v204, v53, v53
	v_fmac_f32_e32 v204, v54, v54
	v_fmac_f32_e32 v204, v55, v55
	v_fmac_f32_e32 v204, v48, v48
	v_fmac_f32_e32 v204, v49, v49
	v_fmac_f32_e32 v204, v50, v50
	v_fmac_f32_e32 v204, v51, v51
	v_add_u32_e32 v211, 0x80000, v209
	v_cvt_pk_bf16_f32 v176, v60, v61
	v_cvt_pk_bf16_f32 v177, v62, v63
	v_cvt_pk_bf16_f32 v178, v56, v57
	v_cvt_pk_bf16_f32 v179, v58, v59
	global_store_dwordx4 v211, v[176:179], s[80:81]
	v_cvt_pk_bf16_f32 v180, v52, v53
	v_cvt_pk_bf16_f32 v181, v54, v55
	v_cvt_pk_bf16_f32 v182, v48, v49
	v_cvt_pk_bf16_f32 v183, v50, v51
	global_store_dwordx4 v211, v[180:183], s[80:81] offset:256
	v_mul_f32_e32 v205, v44, v44
	v_fmac_f32_e32 v205, v45, v45
	v_fmac_f32_e32 v205, v46, v46
	v_fmac_f32_e32 v205, v47, v47
	v_fmac_f32_e32 v205, v40, v40
	v_fmac_f32_e32 v205, v41, v41
	v_fmac_f32_e32 v205, v42, v42
	v_fmac_f32_e32 v205, v43, v43
	v_fmac_f32_e32 v205, v36, v36
	v_fmac_f32_e32 v205, v37, v37
	v_fmac_f32_e32 v205, v38, v38
	v_fmac_f32_e32 v205, v39, v39
	v_fmac_f32_e32 v205, v32, v32
	v_fmac_f32_e32 v205, v33, v33
	v_fmac_f32_e32 v205, v34, v34
	v_fmac_f32_e32 v205, v35, v35
	v_add_u32_e32 v211, 0x90000, v209
	v_cvt_pk_bf16_f32 v184, v44, v45
	v_cvt_pk_bf16_f32 v185, v46, v47
	v_cvt_pk_bf16_f32 v186, v40, v41
	v_cvt_pk_bf16_f32 v187, v42, v43
	global_store_dwordx4 v211, v[184:187], s[80:81]
	v_cvt_pk_bf16_f32 v188, v36, v37
	v_cvt_pk_bf16_f32 v189, v38, v39
	v_cvt_pk_bf16_f32 v190, v32, v33
	v_cvt_pk_bf16_f32 v191, v34, v35
	global_store_dwordx4 v211, v[188:191], s[80:81] offset:256
	v_mul_f32_e32 v206, v28, v28
	v_fmac_f32_e32 v206, v29, v29
	v_fmac_f32_e32 v206, v30, v30
	v_fmac_f32_e32 v206, v31, v31
	v_fmac_f32_e32 v206, v24, v24
	v_fmac_f32_e32 v206, v25, v25
	v_fmac_f32_e32 v206, v26, v26
	v_fmac_f32_e32 v206, v27, v27
	v_fmac_f32_e32 v206, v20, v20
	v_fmac_f32_e32 v206, v21, v21
	v_fmac_f32_e32 v206, v22, v22
	v_fmac_f32_e32 v206, v23, v23
	v_fmac_f32_e32 v206, v16, v16
	v_fmac_f32_e32 v206, v17, v17
	v_fmac_f32_e32 v206, v18, v18
	v_fmac_f32_e32 v206, v19, v19
	v_add_u32_e32 v211, 0xa0000, v209
	v_cvt_pk_bf16_f32 v176, v28, v29
	v_cvt_pk_bf16_f32 v177, v30, v31
	v_cvt_pk_bf16_f32 v178, v24, v25
	v_cvt_pk_bf16_f32 v179, v26, v27
	global_store_dwordx4 v211, v[176:179], s[80:81]
	v_cvt_pk_bf16_f32 v180, v20, v21
	v_cvt_pk_bf16_f32 v181, v22, v23
	v_cvt_pk_bf16_f32 v182, v16, v17
	v_cvt_pk_bf16_f32 v183, v18, v19
	global_store_dwordx4 v211, v[180:183], s[80:81] offset:256
	v_mul_f32_e32 v207, v12, v12
	v_fmac_f32_e32 v207, v13, v13
	v_fmac_f32_e32 v207, v14, v14
	v_fmac_f32_e32 v207, v15, v15
	v_fmac_f32_e32 v207, v8, v8
	v_fmac_f32_e32 v207, v9, v9
	v_fmac_f32_e32 v207, v10, v10
	v_fmac_f32_e32 v207, v11, v11
	v_fmac_f32_e32 v207, v4, v4
	v_fmac_f32_e32 v207, v5, v5
	v_fmac_f32_e32 v207, v6, v6
	v_fmac_f32_e32 v207, v7, v7
	v_fmac_f32_e32 v207, v0, v0
	v_fmac_f32_e32 v207, v1, v1
	v_fmac_f32_e32 v207, v2, v2
	v_fmac_f32_e32 v207, v3, v3
	v_add_u32_e32 v211, 0xb0000, v209
	v_cvt_pk_bf16_f32 v184, v12, v13
	v_cvt_pk_bf16_f32 v185, v14, v15
	v_cvt_pk_bf16_f32 v186, v8, v9
	v_cvt_pk_bf16_f32 v187, v10, v11
	global_store_dwordx4 v211, v[184:187], s[80:81]
	v_cvt_pk_bf16_f32 v188, v4, v5
	v_cvt_pk_bf16_f32 v189, v6, v7
	v_cvt_pk_bf16_f32 v190, v0, v1
	v_cvt_pk_bf16_f32 v191, v2, v3
	global_store_dwordx4 v211, v[188:191], s[80:81] offset:256
	s_nop 1
	ds_bpermute_b32 v192, v213, v200
	ds_bpermute_b32 v193, v213, v201
	ds_bpermute_b32 v194, v213, v202
	ds_bpermute_b32 v195, v213, v203
	ds_bpermute_b32 v196, v213, v204
	ds_bpermute_b32 v197, v213, v205
	ds_bpermute_b32 v198, v213, v206
	ds_bpermute_b32 v199, v213, v207
	s_waitcnt lgkmcnt(0)
	v_add_f32_e32 v200, v200, v192
	v_add_f32_e32 v201, v201, v193
	v_add_f32_e32 v202, v202, v194
	v_add_f32_e32 v203, v203, v195
	v_add_f32_e32 v204, v204, v196
	v_add_f32_e32 v205, v205, v197
	v_add_f32_e32 v206, v206, v198
	v_add_f32_e32 v207, v207, v199
	ds_bpermute_b32 v192, v214, v200
	ds_bpermute_b32 v193, v214, v201
	ds_bpermute_b32 v194, v214, v202
	ds_bpermute_b32 v195, v214, v203
	ds_bpermute_b32 v196, v214, v204
	ds_bpermute_b32 v197, v214, v205
	ds_bpermute_b32 v198, v214, v206
	ds_bpermute_b32 v199, v214, v207
	s_waitcnt lgkmcnt(0)
	v_add_f32_e32 v200, v200, v192
	v_add_f32_e32 v201, v201, v193
	v_add_f32_e32 v202, v202, v194
	v_add_f32_e32 v203, v203, v195
	v_add_f32_e32 v204, v204, v196
	v_add_f32_e32 v205, v205, v197
	v_add_f32_e32 v206, v206, v198
	v_add_f32_e32 v207, v207, v199
	s_mov_b64 exec, 0xffff
	global_atomic_add_f32 v208, v200, s[14:15]
	global_atomic_add_f32 v208, v201, s[14:15] offset:64
	global_atomic_add_f32 v208, v202, s[14:15] offset:128
	global_atomic_add_f32 v208, v203, s[14:15] offset:192
	global_atomic_add_f32 v208, v204, s[14:15] offset:512
	global_atomic_add_f32 v208, v205, s[14:15] offset:576
	global_atomic_add_f32 v208, v206, s[14:15] offset:640
	global_atomic_add_f32 v208, v207, s[14:15] offset:704
	s_mov_b64 exec, -1
	s_branch .LBB0_496

.Lst_out_s7:
	v_lshl_add_u32 v215, s8, 8, v163
	v_add_u32_e32 v215, s35, v215
	v_lshlrev_b32_e32 v208, 2, v215
	v_lshl_add_u32 v212, v225, 3, s36
	v_lshl_add_u32 v212, s0, 8, v212
	v_lshl_add_u32 v209, v215, 11, v212
	v_lshlrev_b32_e32 v209, 1, v209
	v_lshlrev_b32_e32 v210, 1, v209
	v_lshl_add_u32 v215, v225, 4, v163
	v_xor_b32_e32 v213, 16, v215
	v_lshlrev_b32_e32 v213, 2, v213
	v_xor_b32_e32 v214, 32, v215
	v_lshlrev_b32_e32 v214, 2, v214
	v_add_u32_e32 v211, 0x0, v209
	global_load_dwordx4 v[176:179], v211, s[80:81]
	global_load_dwordx4 v[180:183], v211, s[80:81] offset:256
	v_add_u32_e32 v211, 0x10000, v209
	global_load_dwordx4 v[184:187], v211, s[80:81]
	global_load_dwordx4 v[188:191], v211, s[80:81] offset:256
	v_add_u32_e32 v211, 0x20000, v209
	global_load_dwordx4 v[192:195], v211, s[80:81]
	global_load_dwordx4 v[196:199], v211, s[80:81] offset:256
	s_waitcnt vmcnt(4)
	v_lshlrev_b32_e32 v200, 16, v176
	v_and_b32_e32 v201, 0xffff0000, v176
	v_lshlrev_b32_e32 v202, 16, v177
	v_and_b32_e32 v203, 0xffff0000, v177
	v_lshlrev_b32_e32 v204, 16, v178
	v_and_b32_e32 v205, 0xffff0000, v178
	v_lshlrev_b32_e32 v206, 16, v179
	v_and_b32_e32 v207, 0xffff0000, v179
	v_pk_add_f32 v[124:125], v[124:125], v[200:201]
	v_pk_add_f32 v[126:127], v[126:127], v[202:203]
	v_pk_add_f32 v[120:121], v[120:121], v[204:205]
	v_pk_add_f32 v[122:123], v[122:123], v[206:207]
	v_lshlrev_b32_e32 v200, 16, v180
	v_and_b32_e32 v201, 0xffff0000, v180
	v_lshlrev_b32_e32 v202, 16, v181
	v_and_b32_e32 v203, 0xffff0000, v181
	v_lshlrev_b32_e32 v204, 16, v182
	v_and_b32_e32 v205, 0xffff0000, v182
	v_lshlrev_b32_e32 v206, 16, v183
	v_and_b32_e32 v207, 0xffff0000, v183
	v_pk_add_f32 v[116:117], v[116:117], v[200:201]
	v_pk_add_f32 v[118:119], v[118:119], v[202:203]
	v_pk_add_f32 v[112:113], v[112:113], v[204:205]
	v_pk_add_f32 v[114:115], v[114:115], v[206:207]
	v_add_u32_e32 v211, 0x30000, v209
	global_load_dwordx4 v[176:179], v211, s[80:81]
	global_load_dwordx4 v[180:183], v211, s[80:81] offset:256
	s_waitcnt vmcnt(4)
	v_lshlrev_b32_e32 v200, 16, v184
	v_and_b32_e32 v201, 0xffff0000, v184
	v_lshlrev_b32_e32 v202, 16, v185
	v_and_b32_e32 v203, 0xffff0000, v185
	v_lshlrev_b32_e32 v204, 16, v186
	v_and_b32_e32 v205, 0xffff0000, v186
	v_lshlrev_b32_e32 v206, 16, v187
	v_and_b32_e32 v207, 0xffff0000, v187
	v_pk_add_f32 v[108:109], v[108:109], v[200:201]
	v_pk_add_f32 v[110:111], v[110:111], v[202:203]
	v_pk_add_f32 v[104:105], v[104:105], v[204:205]
	v_pk_add_f32 v[106:107], v[106:107], v[206:207]
	v_lshlrev_b32_e32 v200, 16, v188
	v_and_b32_e32 v201, 0xffff0000, v188
	v_lshlrev_b32_e32 v202, 16, v189
	v_and_b32_e32 v203, 0xffff0000, v189
	v_lshlrev_b32_e32 v204, 16, v190
	v_and_b32_e32 v205, 0xffff0000, v190
	v_lshlrev_b32_e32 v206, 16, v191
	v_and_b32_e32 v207, 0xffff0000, v191
	v_pk_add_f32 v[100:101], v[100:101], v[200:201]
	v_pk_add_f32 v[102:103], v[102:103], v[202:203]
	v_pk_add_f32 v[96:97], v[96:97], v[204:205]
	v_pk_add_f32 v[98:99], v[98:99], v[206:207]
	v_add_u32_e32 v211, 0x80000, v209
	global_load_dwordx4 v[184:187], v211, s[80:81]
	global_load_dwordx4 v[188:191], v211, s[80:81] offset:256
	s_waitcnt vmcnt(4)
	v_lshlrev_b32_e32 v200, 16, v192
	v_and_b32_e32 v201, 0xffff0000, v192
	v_lshlrev_b32_e32 v202, 16, v193
	v_and_b32_e32 v203, 0xffff0000, v193
	v_lshlrev_b32_e32 v204, 16, v194
	v_and_b32_e32 v205, 0xffff0000, v194
	v_lshlrev_b32_e32 v206, 16, v195
	v_and_b32_e32 v207, 0xffff0000, v195
	v_pk_add_f32 v[92:93], v[92:93], v[200:201]
	v_pk_add_f32 v[94:95], v[94:95], v[202:203]
	v_pk_add_f32 v[88:89], v[88:89], v[204:205]
	v_pk_add_f32 v[90:91], v[90:91], v[206:207]
	v_lshlrev_b32_e32 v200, 16, v196
	v_and_b32_e32 v201, 0xffff0000, v196
	v_lshlrev_b32_e32 v202, 16, v197
	v_and_b32_e32 v203, 0xffff0000, v197
	v_lshlrev_b32_e32 v204, 16, v198
	v_and_b32_e32 v205, 0xffff0000, v198
	v_lshlrev_b32_e32 v206, 16, v199
	v_and_b32_e32 v207, 0xffff0000, v199
	v_pk_add_f32 v[84:85], v[84:85], v[200:201]
	v_pk_add_f32 v[86:87], v[86:87], v[202:203]
	v_pk_add_f32 v[80:81], v[80:81], v[204:205]
	v_pk_add_f32 v[82:83], v[82:83], v[206:207]
	v_add_u32_e32 v211, 0x90000, v209
	global_load_dwordx4 v[192:195], v211, s[80:81]
	global_load_dwordx4 v[196:199], v211, s[80:81] offset:256
	s_waitcnt vmcnt(4)
	v_lshlrev_b32_e32 v200, 16, v176
	v_and_b32_e32 v201, 0xffff0000, v176
	v_lshlrev_b32_e32 v202, 16, v177
	v_and_b32_e32 v203, 0xffff0000, v177
	v_lshlrev_b32_e32 v204, 16, v178
	v_and_b32_e32 v205, 0xffff0000, v178
	v_lshlrev_b32_e32 v206, 16, v179
	v_and_b32_e32 v207, 0xffff0000, v179
	v_pk_add_f32 v[76:77], v[76:77], v[200:201]
	v_pk_add_f32 v[78:79], v[78:79], v[202:203]
	v_pk_add_f32 v[72:73], v[72:73], v[204:205]
	v_pk_add_f32 v[74:75], v[74:75], v[206:207]
	v_lshlrev_b32_e32 v200, 16, v180
	v_and_b32_e32 v201, 0xffff0000, v180
	v_lshlrev_b32_e32 v202, 16, v181
	v_and_b32_e32 v203, 0xffff0000, v181
	v_lshlrev_b32_e32 v204, 16, v182
	v_and_b32_e32 v205, 0xffff0000, v182
	v_lshlrev_b32_e32 v206, 16, v183
	v_and_b32_e32 v207, 0xffff0000, v183
	v_pk_add_f32 v[68:69], v[68:69], v[200:201]
	v_pk_add_f32 v[70:71], v[70:71], v[202:203]
	v_pk_add_f32 v[64:65], v[64:65], v[204:205]
	v_pk_add_f32 v[66:67], v[66:67], v[206:207]
	v_add_u32_e32 v211, 0xa0000, v209
	global_load_dwordx4 v[176:179], v211, s[80:81]
	global_load_dwordx4 v[180:183], v211, s[80:81] offset:256
	s_waitcnt vmcnt(4)
	v_lshlrev_b32_e32 v200, 16, v184
	v_and_b32_e32 v201, 0xffff0000, v184
	v_lshlrev_b32_e32 v202, 16, v185
	v_and_b32_e32 v203, 0xffff0000, v185
	v_lshlrev_b32_e32 v204, 16, v186
	v_and_b32_e32 v205, 0xffff0000, v186
	v_lshlrev_b32_e32 v206, 16, v187
	v_and_b32_e32 v207, 0xffff0000, v187
	v_pk_add_f32 v[60:61], v[60:61], v[200:201]
	v_pk_add_f32 v[62:63], v[62:63], v[202:203]
	v_pk_add_f32 v[56:57], v[56:57], v[204:205]
	v_pk_add_f32 v[58:59], v[58:59], v[206:207]
	v_lshlrev_b32_e32 v200, 16, v188
	v_and_b32_e32 v201, 0xffff0000, v188
	v_lshlrev_b32_e32 v202, 16, v189
	v_and_b32_e32 v203, 0xffff0000, v189
	v_lshlrev_b32_e32 v204, 16, v190
	v_and_b32_e32 v205, 0xffff0000, v190
	v_lshlrev_b32_e32 v206, 16, v191
	v_and_b32_e32 v207, 0xffff0000, v191
	v_pk_add_f32 v[52:53], v[52:53], v[200:201]
	v_pk_add_f32 v[54:55], v[54:55], v[202:203]
	v_pk_add_f32 v[48:49], v[48:49], v[204:205]
	v_pk_add_f32 v[50:51], v[50:51], v[206:207]
	v_add_u32_e32 v211, 0xb0000, v209
	global_load_dwordx4 v[184:187], v211, s[80:81]
	global_load_dwordx4 v[188:191], v211, s[80:81] offset:256
	s_waitcnt vmcnt(4)
	v_lshlrev_b32_e32 v200, 16, v192
	v_and_b32_e32 v201, 0xffff0000, v192
	v_lshlrev_b32_e32 v202, 16, v193
	v_and_b32_e32 v203, 0xffff0000, v193
	v_lshlrev_b32_e32 v204, 16, v194
	v_and_b32_e32 v205, 0xffff0000, v194
	v_lshlrev_b32_e32 v206, 16, v195
	v_and_b32_e32 v207, 0xffff0000, v195
	v_pk_add_f32 v[44:45], v[44:45], v[200:201]
	v_pk_add_f32 v[46:47], v[46:47], v[202:203]
	v_pk_add_f32 v[40:41], v[40:41], v[204:205]
	v_pk_add_f32 v[42:43], v[42:43], v[206:207]
	v_lshlrev_b32_e32 v200, 16, v196
	v_and_b32_e32 v201, 0xffff0000, v196
	v_lshlrev_b32_e32 v202, 16, v197
	v_and_b32_e32 v203, 0xffff0000, v197
	v_lshlrev_b32_e32 v204, 16, v198
	v_and_b32_e32 v205, 0xffff0000, v198
	v_lshlrev_b32_e32 v206, 16, v199
	v_and_b32_e32 v207, 0xffff0000, v199
	v_pk_add_f32 v[36:37], v[36:37], v[200:201]
	v_pk_add_f32 v[38:39], v[38:39], v[202:203]
	v_pk_add_f32 v[32:33], v[32:33], v[204:205]
	v_pk_add_f32 v[34:35], v[34:35], v[206:207]
	s_waitcnt vmcnt(2)
	v_lshlrev_b32_e32 v200, 16, v176
	v_and_b32_e32 v201, 0xffff0000, v176
	v_lshlrev_b32_e32 v202, 16, v177
	v_and_b32_e32 v203, 0xffff0000, v177
	v_lshlrev_b32_e32 v204, 16, v178
	v_and_b32_e32 v205, 0xffff0000, v178
	v_lshlrev_b32_e32 v206, 16, v179
	v_and_b32_e32 v207, 0xffff0000, v179
	v_pk_add_f32 v[28:29], v[28:29], v[200:201]
	v_pk_add_f32 v[30:31], v[30:31], v[202:203]
	v_pk_add_f32 v[24:25], v[24:25], v[204:205]
	v_pk_add_f32 v[26:27], v[26:27], v[206:207]
	v_lshlrev_b32_e32 v200, 16, v180
	v_and_b32_e32 v201, 0xffff0000, v180
	v_lshlrev_b32_e32 v202, 16, v181
	v_and_b32_e32 v203, 0xffff0000, v181
	v_lshlrev_b32_e32 v204, 16, v182
	v_and_b32_e32 v205, 0xffff0000, v182
	v_lshlrev_b32_e32 v206, 16, v183
	v_and_b32_e32 v207, 0xffff0000, v183
	v_pk_add_f32 v[20:21], v[20:21], v[200:201]
	v_pk_add_f32 v[22:23], v[22:23], v[202:203]
	v_pk_add_f32 v[16:17], v[16:17], v[204:205]
	v_pk_add_f32 v[18:19], v[18:19], v[206:207]
	s_waitcnt vmcnt(0)
	v_lshlrev_b32_e32 v200, 16, v184
	v_and_b32_e32 v201, 0xffff0000, v184
	v_lshlrev_b32_e32 v202, 16, v185
	v_and_b32_e32 v203, 0xffff0000, v185
	v_lshlrev_b32_e32 v204, 16, v186
	v_and_b32_e32 v205, 0xffff0000, v186
	v_lshlrev_b32_e32 v206, 16, v187
	v_and_b32_e32 v207, 0xffff0000, v187
	v_pk_add_f32 v[12:13], v[12:13], v[200:201]
	v_pk_add_f32 v[14:15], v[14:15], v[202:203]
	v_pk_add_f32 v[8:9], v[8:9], v[204:205]
	v_pk_add_f32 v[10:11], v[10:11], v[206:207]
	v_lshlrev_b32_e32 v200, 16, v188
	v_and_b32_e32 v201, 0xffff0000, v188
	v_lshlrev_b32_e32 v202, 16, v189
	v_and_b32_e32 v203, 0xffff0000, v189
	v_lshlrev_b32_e32 v204, 16, v190
	v_and_b32_e32 v205, 0xffff0000, v190
	v_lshlrev_b32_e32 v206, 16, v191
	v_and_b32_e32 v207, 0xffff0000, v191
	v_pk_add_f32 v[4:5], v[4:5], v[200:201]
	v_pk_add_f32 v[6:7], v[6:7], v[202:203]
	v_pk_add_f32 v[0:1], v[0:1], v[204:205]
	v_pk_add_f32 v[2:3], v[2:3], v[206:207]
	v_mul_f32_e32 v200, v124, v124
	v_fmac_f32_e32 v200, v125, v125
	v_fmac_f32_e32 v200, v126, v126
	v_fmac_f32_e32 v200, v127, v127
	v_fmac_f32_e32 v200, v120, v120
	v_fmac_f32_e32 v200, v121, v121
	v_fmac_f32_e32 v200, v122, v122
	v_fmac_f32_e32 v200, v123, v123
	v_fmac_f32_e32 v200, v116, v116
	v_fmac_f32_e32 v200, v117, v117
	v_fmac_f32_e32 v200, v118, v118
	v_fmac_f32_e32 v200, v119, v119
	v_fmac_f32_e32 v200, v112, v112
	v_fmac_f32_e32 v200, v113, v113
	v_fmac_f32_e32 v200, v114, v114
	v_fmac_f32_e32 v200, v115, v115
	v_add_u32_e32 v211, 0x0, v209
	v_cvt_pk_bf16_f32 v176, v124, v125
	v_cvt_pk_bf16_f32 v177, v126, v127
	v_cvt_pk_bf16_f32 v178, v120, v121
	v_cvt_pk_bf16_f32 v179, v122, v123
	global_store_dwordx4 v211, v[176:179], s[80:81]
	v_cvt_pk_bf16_f32 v180, v116, v117
	v_cvt_pk_bf16_f32 v181, v118, v119
	v_cvt_pk_bf16_f32 v182, v112, v113
	v_cvt_pk_bf16_f32 v183, v114, v115
	global_store_dwordx4 v211, v[180:183], s[80:81] offset:256
	v_mul_f32_e32 v201, v108, v108
	v_fmac_f32_e32 v201, v109, v109
	v_fmac_f32_e32 v201, v110, v110
	v_fmac_f32_e32 v201, v111, v111
	v_fmac_f32_e32 v201, v104, v104
	v_fmac_f32_e32 v201, v105, v105
	v_fmac_f32_e32 v201, v106, v106
	v_fmac_f32_e32 v201, v107, v107
	v_fmac_f32_e32 v201, v100, v100
	v_fmac_f32_e32 v201, v101, v101
	v_fmac_f32_e32 v201, v102, v102
	v_fmac_f32_e32 v201, v103, v103
	v_fmac_f32_e32 v201, v96, v96
	v_fmac_f32_e32 v201, v97, v97
	v_fmac_f32_e32 v201, v98, v98
	v_fmac_f32_e32 v201, v99, v99
	v_add_u32_e32 v211, 0x10000, v209
	v_cvt_pk_bf16_f32 v184, v108, v109
	v_cvt_pk_bf16_f32 v185, v110, v111
	v_cvt_pk_bf16_f32 v186, v104, v105
	v_cvt_pk_bf16_f32 v187, v106, v107
	global_store_dwordx4 v211, v[184:187], s[80:81]
	v_cvt_pk_bf16_f32 v188, v100, v101
	v_cvt_pk_bf16_f32 v189, v102, v103
	v_cvt_pk_bf16_f32 v190, v96, v97
	v_cvt_pk_bf16_f32 v191, v98, v99
	global_store_dwordx4 v211, v[188:191], s[80:81] offset:256
	v_mul_f32_e32 v202, v92, v92
	v_fmac_f32_e32 v202, v93, v93
	v_fmac_f32_e32 v202, v94, v94
	v_fmac_f32_e32 v202, v95, v95
	v_fmac_f32_e32 v202, v88, v88
	v_fmac_f32_e32 v202, v89, v89
	v_fmac_f32_e32 v202, v90, v90
	v_fmac_f32_e32 v202, v91, v91
	v_fmac_f32_e32 v202, v84, v84
	v_fmac_f32_e32 v202, v85, v85
	v_fmac_f32_e32 v202, v86, v86
	v_fmac_f32_e32 v202, v87, v87
	v_fmac_f32_e32 v202, v80, v80
	v_fmac_f32_e32 v202, v81, v81
	v_fmac_f32_e32 v202, v82, v82
	v_fmac_f32_e32 v202, v83, v83
	v_add_u32_e32 v211, 0x20000, v209
	v_cvt_pk_bf16_f32 v176, v92, v93
	v_cvt_pk_bf16_f32 v177, v94, v95
	v_cvt_pk_bf16_f32 v178, v88, v89
	v_cvt_pk_bf16_f32 v179, v90, v91
	global_store_dwordx4 v211, v[176:179], s[80:81]
	v_cvt_pk_bf16_f32 v180, v84, v85
	v_cvt_pk_bf16_f32 v181, v86, v87
	v_cvt_pk_bf16_f32 v182, v80, v81
	v_cvt_pk_bf16_f32 v183, v82, v83
	global_store_dwordx4 v211, v[180:183], s[80:81] offset:256
	v_mul_f32_e32 v203, v76, v76
	v_fmac_f32_e32 v203, v77, v77
	v_fmac_f32_e32 v203, v78, v78
	v_fmac_f32_e32 v203, v79, v79
	v_fmac_f32_e32 v203, v72, v72
	v_fmac_f32_e32 v203, v73, v73
	v_fmac_f32_e32 v203, v74, v74
	v_fmac_f32_e32 v203, v75, v75
	v_fmac_f32_e32 v203, v68, v68
	v_fmac_f32_e32 v203, v69, v69
	v_fmac_f32_e32 v203, v70, v70
	v_fmac_f32_e32 v203, v71, v71
	v_fmac_f32_e32 v203, v64, v64
	v_fmac_f32_e32 v203, v65, v65
	v_fmac_f32_e32 v203, v66, v66
	v_fmac_f32_e32 v203, v67, v67
	v_add_u32_e32 v211, 0x30000, v209
	v_cvt_pk_bf16_f32 v184, v76, v77
	v_cvt_pk_bf16_f32 v185, v78, v79
	v_cvt_pk_bf16_f32 v186, v72, v73
	v_cvt_pk_bf16_f32 v187, v74, v75
	global_store_dwordx4 v211, v[184:187], s[80:81]
	v_cvt_pk_bf16_f32 v188, v68, v69
	v_cvt_pk_bf16_f32 v189, v70, v71
	v_cvt_pk_bf16_f32 v190, v64, v65
	v_cvt_pk_bf16_f32 v191, v66, v67
	global_store_dwordx4 v211, v[188:191], s[80:81] offset:256
	v_mul_f32_e32 v204, v60, v60
	v_fmac_f32_e32 v204, v61, v61
	v_fmac_f32_e32 v204, v62, v62
	v_fmac_f32_e32 v204, v63, v63
	v_fmac_f32_e32 v204, v56, v56
	v_fmac_f32_e32 v204, v57, v57
	v_fmac_f32_e32 v204, v58, v58
	v_fmac_f32_e32 v204, v59, v59
	v_fmac_f32_e32 v204, v52, v52
	v_fmac_f32_e32 v204, v53, v53
	v_fmac_f32_e32 v204, v54, v54
	v_fmac_f32_e32 v204, v55, v55
	v_fmac_f32_e32 v204, v48, v48
	v_fmac_f32_e32 v204, v49, v49
	v_fmac_f32_e32 v204, v50, v50
	v_fmac_f32_e32 v204, v51, v51
	v_add_u32_e32 v211, 0x80000, v209
	v_cvt_pk_bf16_f32 v176, v60, v61
	v_cvt_pk_bf16_f32 v177, v62, v63
	v_cvt_pk_bf16_f32 v178, v56, v57
	v_cvt_pk_bf16_f32 v179, v58, v59
	global_store_dwordx4 v211, v[176:179], s[80:81]
	v_cvt_pk_bf16_f32 v180, v52, v53
	v_cvt_pk_bf16_f32 v181, v54, v55
	v_cvt_pk_bf16_f32 v182, v48, v49
	v_cvt_pk_bf16_f32 v183, v50, v51
	global_store_dwordx4 v211, v[180:183], s[80:81] offset:256
	v_mul_f32_e32 v205, v44, v44
	v_fmac_f32_e32 v205, v45, v45
	v_fmac_f32_e32 v205, v46, v46
	v_fmac_f32_e32 v205, v47, v47
	v_fmac_f32_e32 v205, v40, v40
	v_fmac_f32_e32 v205, v41, v41
	v_fmac_f32_e32 v205, v42, v42
	v_fmac_f32_e32 v205, v43, v43
	v_fmac_f32_e32 v205, v36, v36
	v_fmac_f32_e32 v205, v37, v37
	v_fmac_f32_e32 v205, v38, v38
	v_fmac_f32_e32 v205, v39, v39
	v_fmac_f32_e32 v205, v32, v32
	v_fmac_f32_e32 v205, v33, v33
	v_fmac_f32_e32 v205, v34, v34
	v_fmac_f32_e32 v205, v35, v35
	v_add_u32_e32 v211, 0x90000, v209
	v_cvt_pk_bf16_f32 v184, v44, v45
	v_cvt_pk_bf16_f32 v185, v46, v47
	v_cvt_pk_bf16_f32 v186, v40, v41
	v_cvt_pk_bf16_f32 v187, v42, v43
	global_store_dwordx4 v211, v[184:187], s[80:81]
	v_cvt_pk_bf16_f32 v188, v36, v37
	v_cvt_pk_bf16_f32 v189, v38, v39
	v_cvt_pk_bf16_f32 v190, v32, v33
	v_cvt_pk_bf16_f32 v191, v34, v35
	global_store_dwordx4 v211, v[188:191], s[80:81] offset:256
	v_mul_f32_e32 v206, v28, v28
	v_fmac_f32_e32 v206, v29, v29
	v_fmac_f32_e32 v206, v30, v30
	v_fmac_f32_e32 v206, v31, v31
	v_fmac_f32_e32 v206, v24, v24
	v_fmac_f32_e32 v206, v25, v25
	v_fmac_f32_e32 v206, v26, v26
	v_fmac_f32_e32 v206, v27, v27
	v_fmac_f32_e32 v206, v20, v20
	v_fmac_f32_e32 v206, v21, v21
	v_fmac_f32_e32 v206, v22, v22
	v_fmac_f32_e32 v206, v23, v23
	v_fmac_f32_e32 v206, v16, v16
	v_fmac_f32_e32 v206, v17, v17
	v_fmac_f32_e32 v206, v18, v18
	v_fmac_f32_e32 v206, v19, v19
	v_add_u32_e32 v211, 0xa0000, v209
	v_cvt_pk_bf16_f32 v176, v28, v29
	v_cvt_pk_bf16_f32 v177, v30, v31
	v_cvt_pk_bf16_f32 v178, v24, v25
	v_cvt_pk_bf16_f32 v179, v26, v27
	global_store_dwordx4 v211, v[176:179], s[80:81]
	v_cvt_pk_bf16_f32 v180, v20, v21
	v_cvt_pk_bf16_f32 v181, v22, v23
	v_cvt_pk_bf16_f32 v182, v16, v17
	v_cvt_pk_bf16_f32 v183, v18, v19
	global_store_dwordx4 v211, v[180:183], s[80:81] offset:256
	v_mul_f32_e32 v207, v12, v12
	v_fmac_f32_e32 v207, v13, v13
	v_fmac_f32_e32 v207, v14, v14
	v_fmac_f32_e32 v207, v15, v15
	v_fmac_f32_e32 v207, v8, v8
	v_fmac_f32_e32 v207, v9, v9
	v_fmac_f32_e32 v207, v10, v10
	v_fmac_f32_e32 v207, v11, v11
	v_fmac_f32_e32 v207, v4, v4
	v_fmac_f32_e32 v207, v5, v5
	v_fmac_f32_e32 v207, v6, v6
	v_fmac_f32_e32 v207, v7, v7
	v_fmac_f32_e32 v207, v0, v0
	v_fmac_f32_e32 v207, v1, v1
	v_fmac_f32_e32 v207, v2, v2
	v_fmac_f32_e32 v207, v3, v3
	v_add_u32_e32 v211, 0xb0000, v209
	v_cvt_pk_bf16_f32 v184, v12, v13
	v_cvt_pk_bf16_f32 v185, v14, v15
	v_cvt_pk_bf16_f32 v186, v8, v9
	v_cvt_pk_bf16_f32 v187, v10, v11
	global_store_dwordx4 v211, v[184:187], s[80:81]
	v_cvt_pk_bf16_f32 v188, v4, v5
	v_cvt_pk_bf16_f32 v189, v6, v7
	v_cvt_pk_bf16_f32 v190, v0, v1
	v_cvt_pk_bf16_f32 v191, v2, v3
	global_store_dwordx4 v211, v[188:191], s[80:81] offset:256
	s_nop 1
	ds_bpermute_b32 v192, v213, v200
	ds_bpermute_b32 v193, v213, v201
	ds_bpermute_b32 v194, v213, v202
	ds_bpermute_b32 v195, v213, v203
	ds_bpermute_b32 v196, v213, v204
	ds_bpermute_b32 v197, v213, v205
	ds_bpermute_b32 v198, v213, v206
	ds_bpermute_b32 v199, v213, v207
	s_waitcnt lgkmcnt(0)
	v_add_f32_e32 v200, v200, v192
	v_add_f32_e32 v201, v201, v193
	v_add_f32_e32 v202, v202, v194
	v_add_f32_e32 v203, v203, v195
	v_add_f32_e32 v204, v204, v196
	v_add_f32_e32 v205, v205, v197
	v_add_f32_e32 v206, v206, v198
	v_add_f32_e32 v207, v207, v199
	ds_bpermute_b32 v192, v214, v200
	ds_bpermute_b32 v193, v214, v201
	ds_bpermute_b32 v194, v214, v202
	ds_bpermute_b32 v195, v214, v203
	ds_bpermute_b32 v196, v214, v204
	ds_bpermute_b32 v197, v214, v205
	ds_bpermute_b32 v198, v214, v206
	ds_bpermute_b32 v199, v214, v207
	s_waitcnt lgkmcnt(0)
	v_add_f32_e32 v200, v200, v192
	v_add_f32_e32 v201, v201, v193
	v_add_f32_e32 v202, v202, v194
	v_add_f32_e32 v203, v203, v195
	v_add_f32_e32 v204, v204, v196
	v_add_f32_e32 v205, v205, v197
	v_add_f32_e32 v206, v206, v198
	v_add_f32_e32 v207, v207, v199
	s_mov_b64 exec, 0xffff
	global_atomic_add_f32 v208, v200, s[4:5]
	global_atomic_add_f32 v208, v201, s[4:5] offset:64
	global_atomic_add_f32 v208, v202, s[4:5] offset:128
	global_atomic_add_f32 v208, v203, s[4:5] offset:192
	global_atomic_add_f32 v208, v204, s[4:5] offset:512
	global_atomic_add_f32 v208, v205, s[4:5] offset:576
	global_atomic_add_f32 v208, v206, s[4:5] offset:640
	global_atomic_add_f32 v208, v207, s[4:5] offset:704
	s_mov_b64 exec, -1
	s_branch .LBB0_752

.Lst_out_s9:
	v_lshl_add_u32 v215, s38, 8, v163
	v_add_u32_e32 v215, s26, v215
	v_lshlrev_b32_e32 v208, 2, v215
	v_lshl_add_u32 v212, v225, 3, s27
	v_lshl_add_u32 v212, s37, 8, v212
	v_lshl_add_u32 v209, v215, 11, v212
	v_lshlrev_b32_e32 v209, 1, v209
	v_lshlrev_b32_e32 v210, 1, v209
	v_lshl_add_u32 v215, v225, 4, v163
	v_xor_b32_e32 v213, 16, v215
	v_lshlrev_b32_e32 v213, 2, v213
	v_xor_b32_e32 v214, 32, v215
	v_lshlrev_b32_e32 v214, 2, v214
	v_add_u32_e32 v211, 0x0, v209
	global_load_dwordx4 v[176:179], v211, s[80:81]
	global_load_dwordx4 v[180:183], v211, s[80:81] offset:256
	v_add_u32_e32 v211, 0x10000, v209
	global_load_dwordx4 v[184:187], v211, s[80:81]
	global_load_dwordx4 v[188:191], v211, s[80:81] offset:256
	v_add_u32_e32 v211, 0x20000, v209
	global_load_dwordx4 v[192:195], v211, s[80:81]
	global_load_dwordx4 v[196:199], v211, s[80:81] offset:256
	s_waitcnt vmcnt(4)
	v_lshlrev_b32_e32 v200, 16, v176
	v_and_b32_e32 v201, 0xffff0000, v176
	v_lshlrev_b32_e32 v202, 16, v177
	v_and_b32_e32 v203, 0xffff0000, v177
	v_lshlrev_b32_e32 v204, 16, v178
	v_and_b32_e32 v205, 0xffff0000, v178
	v_lshlrev_b32_e32 v206, 16, v179
	v_and_b32_e32 v207, 0xffff0000, v179
	v_pk_add_f32 v[124:125], v[124:125], v[200:201]
	v_pk_add_f32 v[126:127], v[126:127], v[202:203]
	v_pk_add_f32 v[120:121], v[120:121], v[204:205]
	v_pk_add_f32 v[122:123], v[122:123], v[206:207]
	v_lshlrev_b32_e32 v200, 16, v180
	v_and_b32_e32 v201, 0xffff0000, v180
	v_lshlrev_b32_e32 v202, 16, v181
	v_and_b32_e32 v203, 0xffff0000, v181
	v_lshlrev_b32_e32 v204, 16, v182
	v_and_b32_e32 v205, 0xffff0000, v182
	v_lshlrev_b32_e32 v206, 16, v183
	v_and_b32_e32 v207, 0xffff0000, v183
	v_pk_add_f32 v[116:117], v[116:117], v[200:201]
	v_pk_add_f32 v[118:119], v[118:119], v[202:203]
	v_pk_add_f32 v[112:113], v[112:113], v[204:205]
	v_pk_add_f32 v[114:115], v[114:115], v[206:207]
	v_add_u32_e32 v211, 0x30000, v209
	global_load_dwordx4 v[176:179], v211, s[80:81]
	global_load_dwordx4 v[180:183], v211, s[80:81] offset:256
	s_waitcnt vmcnt(4)
	v_lshlrev_b32_e32 v200, 16, v184
	v_and_b32_e32 v201, 0xffff0000, v184
	v_lshlrev_b32_e32 v202, 16, v185
	v_and_b32_e32 v203, 0xffff0000, v185
	v_lshlrev_b32_e32 v204, 16, v186
	v_and_b32_e32 v205, 0xffff0000, v186
	v_lshlrev_b32_e32 v206, 16, v187
	v_and_b32_e32 v207, 0xffff0000, v187
	v_pk_add_f32 v[108:109], v[108:109], v[200:201]
	v_pk_add_f32 v[110:111], v[110:111], v[202:203]
	v_pk_add_f32 v[104:105], v[104:105], v[204:205]
	v_pk_add_f32 v[106:107], v[106:107], v[206:207]
	v_lshlrev_b32_e32 v200, 16, v188
	v_and_b32_e32 v201, 0xffff0000, v188
	v_lshlrev_b32_e32 v202, 16, v189
	v_and_b32_e32 v203, 0xffff0000, v189
	v_lshlrev_b32_e32 v204, 16, v190
	v_and_b32_e32 v205, 0xffff0000, v190
	v_lshlrev_b32_e32 v206, 16, v191
	v_and_b32_e32 v207, 0xffff0000, v191
	v_pk_add_f32 v[100:101], v[100:101], v[200:201]
	v_pk_add_f32 v[102:103], v[102:103], v[202:203]
	v_pk_add_f32 v[96:97], v[96:97], v[204:205]
	v_pk_add_f32 v[98:99], v[98:99], v[206:207]
	v_add_u32_e32 v211, 0x80000, v209
	global_load_dwordx4 v[184:187], v211, s[80:81]
	global_load_dwordx4 v[188:191], v211, s[80:81] offset:256
	s_waitcnt vmcnt(4)
	v_lshlrev_b32_e32 v200, 16, v192
	v_and_b32_e32 v201, 0xffff0000, v192
	v_lshlrev_b32_e32 v202, 16, v193
	v_and_b32_e32 v203, 0xffff0000, v193
	v_lshlrev_b32_e32 v204, 16, v194
	v_and_b32_e32 v205, 0xffff0000, v194
	v_lshlrev_b32_e32 v206, 16, v195
	v_and_b32_e32 v207, 0xffff0000, v195
	v_pk_add_f32 v[92:93], v[92:93], v[200:201]
	v_pk_add_f32 v[94:95], v[94:95], v[202:203]
	v_pk_add_f32 v[88:89], v[88:89], v[204:205]
	v_pk_add_f32 v[90:91], v[90:91], v[206:207]
	v_lshlrev_b32_e32 v200, 16, v196
	v_and_b32_e32 v201, 0xffff0000, v196
	v_lshlrev_b32_e32 v202, 16, v197
	v_and_b32_e32 v203, 0xffff0000, v197
	v_lshlrev_b32_e32 v204, 16, v198
	v_and_b32_e32 v205, 0xffff0000, v198
	v_lshlrev_b32_e32 v206, 16, v199
	v_and_b32_e32 v207, 0xffff0000, v199
	v_pk_add_f32 v[84:85], v[84:85], v[200:201]
	v_pk_add_f32 v[86:87], v[86:87], v[202:203]
	v_pk_add_f32 v[80:81], v[80:81], v[204:205]
	v_pk_add_f32 v[82:83], v[82:83], v[206:207]
	v_add_u32_e32 v211, 0x90000, v209
	global_load_dwordx4 v[192:195], v211, s[80:81]
	global_load_dwordx4 v[196:199], v211, s[80:81] offset:256
	s_waitcnt vmcnt(4)
	v_lshlrev_b32_e32 v200, 16, v176
	v_and_b32_e32 v201, 0xffff0000, v176
	v_lshlrev_b32_e32 v202, 16, v177
	v_and_b32_e32 v203, 0xffff0000, v177
	v_lshlrev_b32_e32 v204, 16, v178
	v_and_b32_e32 v205, 0xffff0000, v178
	v_lshlrev_b32_e32 v206, 16, v179
	v_and_b32_e32 v207, 0xffff0000, v179
	v_pk_add_f32 v[76:77], v[76:77], v[200:201]
	v_pk_add_f32 v[78:79], v[78:79], v[202:203]
	v_pk_add_f32 v[72:73], v[72:73], v[204:205]
	v_pk_add_f32 v[74:75], v[74:75], v[206:207]
	v_lshlrev_b32_e32 v200, 16, v180
	v_and_b32_e32 v201, 0xffff0000, v180
	v_lshlrev_b32_e32 v202, 16, v181
	v_and_b32_e32 v203, 0xffff0000, v181
	v_lshlrev_b32_e32 v204, 16, v182
	v_and_b32_e32 v205, 0xffff0000, v182
	v_lshlrev_b32_e32 v206, 16, v183
	v_and_b32_e32 v207, 0xffff0000, v183
	v_pk_add_f32 v[68:69], v[68:69], v[200:201]
	v_pk_add_f32 v[70:71], v[70:71], v[202:203]
	v_pk_add_f32 v[64:65], v[64:65], v[204:205]
	v_pk_add_f32 v[66:67], v[66:67], v[206:207]
	v_add_u32_e32 v211, 0xa0000, v209
	global_load_dwordx4 v[176:179], v211, s[80:81]
	global_load_dwordx4 v[180:183], v211, s[80:81] offset:256
	s_waitcnt vmcnt(4)
	v_lshlrev_b32_e32 v200, 16, v184
	v_and_b32_e32 v201, 0xffff0000, v184
	v_lshlrev_b32_e32 v202, 16, v185
	v_and_b32_e32 v203, 0xffff0000, v185
	v_lshlrev_b32_e32 v204, 16, v186
	v_and_b32_e32 v205, 0xffff0000, v186
	v_lshlrev_b32_e32 v206, 16, v187
	v_and_b32_e32 v207, 0xffff0000, v187
	v_pk_add_f32 v[60:61], v[60:61], v[200:201]
	v_pk_add_f32 v[62:63], v[62:63], v[202:203]
	v_pk_add_f32 v[56:57], v[56:57], v[204:205]
	v_pk_add_f32 v[58:59], v[58:59], v[206:207]
	v_lshlrev_b32_e32 v200, 16, v188
	v_and_b32_e32 v201, 0xffff0000, v188
	v_lshlrev_b32_e32 v202, 16, v189
	v_and_b32_e32 v203, 0xffff0000, v189
	v_lshlrev_b32_e32 v204, 16, v190
	v_and_b32_e32 v205, 0xffff0000, v190
	v_lshlrev_b32_e32 v206, 16, v191
	v_and_b32_e32 v207, 0xffff0000, v191
	v_pk_add_f32 v[52:53], v[52:53], v[200:201]
	v_pk_add_f32 v[54:55], v[54:55], v[202:203]
	v_pk_add_f32 v[48:49], v[48:49], v[204:205]
	v_pk_add_f32 v[50:51], v[50:51], v[206:207]
	v_add_u32_e32 v211, 0xb0000, v209
	global_load_dwordx4 v[184:187], v211, s[80:81]
	global_load_dwordx4 v[188:191], v211, s[80:81] offset:256
	s_waitcnt vmcnt(4)
	v_lshlrev_b32_e32 v200, 16, v192
	v_and_b32_e32 v201, 0xffff0000, v192
	v_lshlrev_b32_e32 v202, 16, v193
	v_and_b32_e32 v203, 0xffff0000, v193
	v_lshlrev_b32_e32 v204, 16, v194
	v_and_b32_e32 v205, 0xffff0000, v194
	v_lshlrev_b32_e32 v206, 16, v195
	v_and_b32_e32 v207, 0xffff0000, v195
	v_pk_add_f32 v[44:45], v[44:45], v[200:201]
	v_pk_add_f32 v[46:47], v[46:47], v[202:203]
	v_pk_add_f32 v[40:41], v[40:41], v[204:205]
	v_pk_add_f32 v[42:43], v[42:43], v[206:207]
	v_lshlrev_b32_e32 v200, 16, v196
	v_and_b32_e32 v201, 0xffff0000, v196
	v_lshlrev_b32_e32 v202, 16, v197
	v_and_b32_e32 v203, 0xffff0000, v197
	v_lshlrev_b32_e32 v204, 16, v198
	v_and_b32_e32 v205, 0xffff0000, v198
	v_lshlrev_b32_e32 v206, 16, v199
	v_and_b32_e32 v207, 0xffff0000, v199
	v_pk_add_f32 v[36:37], v[36:37], v[200:201]
	v_pk_add_f32 v[38:39], v[38:39], v[202:203]
	v_pk_add_f32 v[32:33], v[32:33], v[204:205]
	v_pk_add_f32 v[34:35], v[34:35], v[206:207]
	s_waitcnt vmcnt(2)
	v_lshlrev_b32_e32 v200, 16, v176
	v_and_b32_e32 v201, 0xffff0000, v176
	v_lshlrev_b32_e32 v202, 16, v177
	v_and_b32_e32 v203, 0xffff0000, v177
	v_lshlrev_b32_e32 v204, 16, v178
	v_and_b32_e32 v205, 0xffff0000, v178
	v_lshlrev_b32_e32 v206, 16, v179
	v_and_b32_e32 v207, 0xffff0000, v179
	v_pk_add_f32 v[28:29], v[28:29], v[200:201]
	v_pk_add_f32 v[30:31], v[30:31], v[202:203]
	v_pk_add_f32 v[24:25], v[24:25], v[204:205]
	v_pk_add_f32 v[26:27], v[26:27], v[206:207]
	v_lshlrev_b32_e32 v200, 16, v180
	v_and_b32_e32 v201, 0xffff0000, v180
	v_lshlrev_b32_e32 v202, 16, v181
	v_and_b32_e32 v203, 0xffff0000, v181
	v_lshlrev_b32_e32 v204, 16, v182
	v_and_b32_e32 v205, 0xffff0000, v182
	v_lshlrev_b32_e32 v206, 16, v183
	v_and_b32_e32 v207, 0xffff0000, v183
	v_pk_add_f32 v[20:21], v[20:21], v[200:201]
	v_pk_add_f32 v[22:23], v[22:23], v[202:203]
	v_pk_add_f32 v[16:17], v[16:17], v[204:205]
	v_pk_add_f32 v[18:19], v[18:19], v[206:207]
	s_waitcnt vmcnt(0)
	v_lshlrev_b32_e32 v200, 16, v184
	v_and_b32_e32 v201, 0xffff0000, v184
	v_lshlrev_b32_e32 v202, 16, v185
	v_and_b32_e32 v203, 0xffff0000, v185
	v_lshlrev_b32_e32 v204, 16, v186
	v_and_b32_e32 v205, 0xffff0000, v186
	v_lshlrev_b32_e32 v206, 16, v187
	v_and_b32_e32 v207, 0xffff0000, v187
	v_pk_add_f32 v[12:13], v[12:13], v[200:201]
	v_pk_add_f32 v[14:15], v[14:15], v[202:203]
	v_pk_add_f32 v[8:9], v[8:9], v[204:205]
	v_pk_add_f32 v[10:11], v[10:11], v[206:207]
	v_lshlrev_b32_e32 v200, 16, v188
	v_and_b32_e32 v201, 0xffff0000, v188
	v_lshlrev_b32_e32 v202, 16, v189
	v_and_b32_e32 v203, 0xffff0000, v189
	v_lshlrev_b32_e32 v204, 16, v190
	v_and_b32_e32 v205, 0xffff0000, v190
	v_lshlrev_b32_e32 v206, 16, v191
	v_and_b32_e32 v207, 0xffff0000, v191
	v_pk_add_f32 v[4:5], v[4:5], v[200:201]
	v_pk_add_f32 v[6:7], v[6:7], v[202:203]
	v_pk_add_f32 v[0:1], v[0:1], v[204:205]
	v_pk_add_f32 v[2:3], v[2:3], v[206:207]
	v_mul_f32_e32 v200, v124, v124
	v_fmac_f32_e32 v200, v125, v125
	v_fmac_f32_e32 v200, v126, v126
	v_fmac_f32_e32 v200, v127, v127
	v_fmac_f32_e32 v200, v120, v120
	v_fmac_f32_e32 v200, v121, v121
	v_fmac_f32_e32 v200, v122, v122
	v_fmac_f32_e32 v200, v123, v123
	v_fmac_f32_e32 v200, v116, v116
	v_fmac_f32_e32 v200, v117, v117
	v_fmac_f32_e32 v200, v118, v118
	v_fmac_f32_e32 v200, v119, v119
	v_fmac_f32_e32 v200, v112, v112
	v_fmac_f32_e32 v200, v113, v113
	v_fmac_f32_e32 v200, v114, v114
	v_fmac_f32_e32 v200, v115, v115
	v_add_u32_e32 v211, 0x0, v210
	global_store_dwordx4 v211, v[124:127], s[90:91]
	global_store_dwordx4 v211, v[120:123], s[90:91] offset:16
	global_store_dwordx4 v211, v[116:119], s[90:91] offset:512
	global_store_dwordx4 v211, v[112:115], s[90:91] offset:528
	v_mul_f32_e32 v201, v108, v108
	v_fmac_f32_e32 v201, v109, v109
	v_fmac_f32_e32 v201, v110, v110
	v_fmac_f32_e32 v201, v111, v111
	v_fmac_f32_e32 v201, v104, v104
	v_fmac_f32_e32 v201, v105, v105
	v_fmac_f32_e32 v201, v106, v106
	v_fmac_f32_e32 v201, v107, v107
	v_fmac_f32_e32 v201, v100, v100
	v_fmac_f32_e32 v201, v101, v101
	v_fmac_f32_e32 v201, v102, v102
	v_fmac_f32_e32 v201, v103, v103
	v_fmac_f32_e32 v201, v96, v96
	v_fmac_f32_e32 v201, v97, v97
	v_fmac_f32_e32 v201, v98, v98
	v_fmac_f32_e32 v201, v99, v99
	v_add_u32_e32 v211, 0x20000, v210
	global_store_dwordx4 v211, v[108:111], s[90:91]
	global_store_dwordx4 v211, v[104:107], s[90:91] offset:16
	global_store_dwordx4 v211, v[100:103], s[90:91] offset:512
	global_store_dwordx4 v211, v[96:99], s[90:91] offset:528
	v_mul_f32_e32 v202, v92, v92
	v_fmac_f32_e32 v202, v93, v93
	v_fmac_f32_e32 v202, v94, v94
	v_fmac_f32_e32 v202, v95, v95
	v_fmac_f32_e32 v202, v88, v88
	v_fmac_f32_e32 v202, v89, v89
	v_fmac_f32_e32 v202, v90, v90
	v_fmac_f32_e32 v202, v91, v91
	v_fmac_f32_e32 v202, v84, v84
	v_fmac_f32_e32 v202, v85, v85
	v_fmac_f32_e32 v202, v86, v86
	v_fmac_f32_e32 v202, v87, v87
	v_fmac_f32_e32 v202, v80, v80
	v_fmac_f32_e32 v202, v81, v81
	v_fmac_f32_e32 v202, v82, v82
	v_fmac_f32_e32 v202, v83, v83
	v_add_u32_e32 v211, 0x40000, v210
	global_store_dwordx4 v211, v[92:95], s[90:91]
	global_store_dwordx4 v211, v[88:91], s[90:91] offset:16
	global_store_dwordx4 v211, v[84:87], s[90:91] offset:512
	global_store_dwordx4 v211, v[80:83], s[90:91] offset:528
	v_mul_f32_e32 v203, v76, v76
	v_fmac_f32_e32 v203, v77, v77
	v_fmac_f32_e32 v203, v78, v78
	v_fmac_f32_e32 v203, v79, v79
	v_fmac_f32_e32 v203, v72, v72
	v_fmac_f32_e32 v203, v73, v73
	v_fmac_f32_e32 v203, v74, v74
	v_fmac_f32_e32 v203, v75, v75
	v_fmac_f32_e32 v203, v68, v68
	v_fmac_f32_e32 v203, v69, v69
	v_fmac_f32_e32 v203, v70, v70
	v_fmac_f32_e32 v203, v71, v71
	v_fmac_f32_e32 v203, v64, v64
	v_fmac_f32_e32 v203, v65, v65
	v_fmac_f32_e32 v203, v66, v66
	v_fmac_f32_e32 v203, v67, v67
	v_add_u32_e32 v211, 0x60000, v210
	global_store_dwordx4 v211, v[76:79], s[90:91]
	global_store_dwordx4 v211, v[72:75], s[90:91] offset:16
	global_store_dwordx4 v211, v[68:71], s[90:91] offset:512
	global_store_dwordx4 v211, v[64:67], s[90:91] offset:528
	v_mul_f32_e32 v204, v60, v60
	v_fmac_f32_e32 v204, v61, v61
	v_fmac_f32_e32 v204, v62, v62
	v_fmac_f32_e32 v204, v63, v63
	v_fmac_f32_e32 v204, v56, v56
	v_fmac_f32_e32 v204, v57, v57
	v_fmac_f32_e32 v204, v58, v58
	v_fmac_f32_e32 v204, v59, v59
	v_fmac_f32_e32 v204, v52, v52
	v_fmac_f32_e32 v204, v53, v53
	v_fmac_f32_e32 v204, v54, v54
	v_fmac_f32_e32 v204, v55, v55
	v_fmac_f32_e32 v204, v48, v48
	v_fmac_f32_e32 v204, v49, v49
	v_fmac_f32_e32 v204, v50, v50
	v_fmac_f32_e32 v204, v51, v51
	v_add_u32_e32 v211, 0x100000, v210
	global_store_dwordx4 v211, v[60:63], s[90:91]
	global_store_dwordx4 v211, v[56:59], s[90:91] offset:16
	global_store_dwordx4 v211, v[52:55], s[90:91] offset:512
	global_store_dwordx4 v211, v[48:51], s[90:91] offset:528
	v_mul_f32_e32 v205, v44, v44
	v_fmac_f32_e32 v205, v45, v45
	v_fmac_f32_e32 v205, v46, v46
	v_fmac_f32_e32 v205, v47, v47
	v_fmac_f32_e32 v205, v40, v40
	v_fmac_f32_e32 v205, v41, v41
	v_fmac_f32_e32 v205, v42, v42
	v_fmac_f32_e32 v205, v43, v43
	v_fmac_f32_e32 v205, v36, v36
	v_fmac_f32_e32 v205, v37, v37
	v_fmac_f32_e32 v205, v38, v38
	v_fmac_f32_e32 v205, v39, v39
	v_fmac_f32_e32 v205, v32, v32
	v_fmac_f32_e32 v205, v33, v33
	v_fmac_f32_e32 v205, v34, v34
	v_fmac_f32_e32 v205, v35, v35
	v_add_u32_e32 v211, 0x120000, v210
	global_store_dwordx4 v211, v[44:47], s[90:91]
	global_store_dwordx4 v211, v[40:43], s[90:91] offset:16
	global_store_dwordx4 v211, v[36:39], s[90:91] offset:512
	global_store_dwordx4 v211, v[32:35], s[90:91] offset:528
	v_mul_f32_e32 v206, v28, v28
	v_fmac_f32_e32 v206, v29, v29
	v_fmac_f32_e32 v206, v30, v30
	v_fmac_f32_e32 v206, v31, v31
	v_fmac_f32_e32 v206, v24, v24
	v_fmac_f32_e32 v206, v25, v25
	v_fmac_f32_e32 v206, v26, v26
	v_fmac_f32_e32 v206, v27, v27
	v_fmac_f32_e32 v206, v20, v20
	v_fmac_f32_e32 v206, v21, v21
	v_fmac_f32_e32 v206, v22, v22
	v_fmac_f32_e32 v206, v23, v23
	v_fmac_f32_e32 v206, v16, v16
	v_fmac_f32_e32 v206, v17, v17
	v_fmac_f32_e32 v206, v18, v18
	v_fmac_f32_e32 v206, v19, v19
	v_add_u32_e32 v211, 0x140000, v210
	global_store_dwordx4 v211, v[28:31], s[90:91]
	global_store_dwordx4 v211, v[24:27], s[90:91] offset:16
	global_store_dwordx4 v211, v[20:23], s[90:91] offset:512
	global_store_dwordx4 v211, v[16:19], s[90:91] offset:528
	v_mul_f32_e32 v207, v12, v12
	v_fmac_f32_e32 v207, v13, v13
	v_fmac_f32_e32 v207, v14, v14
	v_fmac_f32_e32 v207, v15, v15
	v_fmac_f32_e32 v207, v8, v8
	v_fmac_f32_e32 v207, v9, v9
	v_fmac_f32_e32 v207, v10, v10
	v_fmac_f32_e32 v207, v11, v11
	v_fmac_f32_e32 v207, v4, v4
	v_fmac_f32_e32 v207, v5, v5
	v_fmac_f32_e32 v207, v6, v6
	v_fmac_f32_e32 v207, v7, v7
	v_fmac_f32_e32 v207, v0, v0
	v_fmac_f32_e32 v207, v1, v1
	v_fmac_f32_e32 v207, v2, v2
	v_fmac_f32_e32 v207, v3, v3
	v_add_u32_e32 v211, 0x160000, v210
	global_store_dwordx4 v211, v[12:15], s[90:91]
	global_store_dwordx4 v211, v[8:11], s[90:91] offset:16
	global_store_dwordx4 v211, v[4:7], s[90:91] offset:512
	global_store_dwordx4 v211, v[0:3], s[90:91] offset:528
	s_nop 1
	ds_bpermute_b32 v192, v213, v200
	ds_bpermute_b32 v193, v213, v201
	ds_bpermute_b32 v194, v213, v202
	ds_bpermute_b32 v195, v213, v203
	ds_bpermute_b32 v196, v213, v204
	ds_bpermute_b32 v197, v213, v205
	ds_bpermute_b32 v198, v213, v206
	ds_bpermute_b32 v199, v213, v207
	s_waitcnt lgkmcnt(0)
	v_add_f32_e32 v200, v200, v192
	v_add_f32_e32 v201, v201, v193
	v_add_f32_e32 v202, v202, v194
	v_add_f32_e32 v203, v203, v195
	v_add_f32_e32 v204, v204, v196
	v_add_f32_e32 v205, v205, v197
	v_add_f32_e32 v206, v206, v198
	v_add_f32_e32 v207, v207, v199
	ds_bpermute_b32 v192, v214, v200
	ds_bpermute_b32 v193, v214, v201
	ds_bpermute_b32 v194, v214, v202
	ds_bpermute_b32 v195, v214, v203
	ds_bpermute_b32 v196, v214, v204
	ds_bpermute_b32 v197, v214, v205
	ds_bpermute_b32 v198, v214, v206
	ds_bpermute_b32 v199, v214, v207
	s_waitcnt lgkmcnt(0)
	v_add_f32_e32 v200, v200, v192
	v_add_f32_e32 v201, v201, v193
	v_add_f32_e32 v202, v202, v194
	v_add_f32_e32 v203, v203, v195
	v_add_f32_e32 v204, v204, v196
	v_add_f32_e32 v205, v205, v197
	v_add_f32_e32 v206, v206, v198
	v_add_f32_e32 v207, v207, v199
	s_mov_b64 exec, 0xffff
	global_atomic_add_f32 v208, v200, s[10:11]
	global_atomic_add_f32 v208, v201, s[10:11] offset:64
	global_atomic_add_f32 v208, v202, s[10:11] offset:128
	global_atomic_add_f32 v208, v203, s[10:11] offset:192
	global_atomic_add_f32 v208, v204, s[10:11] offset:512
	global_atomic_add_f32 v208, v205, s[10:11] offset:576
	global_atomic_add_f32 v208, v206, s[10:11] offset:640
	global_atomic_add_f32 v208, v207, s[10:11] offset:704
	s_mov_b64 exec, -1
	s_branch .LBB0_973
